# P1 FProj epilogue specialised per column-tile class (type dispatch resolved once per tile by partial evaluation; dead flag ops removed), on top of combined build
# speedup vs baseline: 1.0322x; 1.0094x over previous
; #define GAS __attribute__((address_space(1)))
; __device__ __forceinline__ float bf_lo(unsigned w) { return __uint_as_float(w << 16); }
; __device__ __forceinline__ float bf_hi(unsigned w) { return __uint_as_float(w & 0xffff0000u); }
;     __device__ __forceinline__ void operator()(const f32x4 (&acc)[2][2][4][2], const Unit& u, int wr, int wc, int fr, int fq) const {
; #pragma unroll
;         for (int ai = 0; ai < 2; ++ai)
; #pragma unroll
;             for (int m = 0; m < 4; ++m) {
;                 const int row = u.pm * BM + ai * HALF + wr * 64 + m * 16 + fr;
; #pragma unroll
;                 for (int bj = 0; bj < 2; ++bj) f(u, row, bj * HALF + wc * 32 + 8 * fq, acc[ai][bj][m][0], acc[ai][bj][m][1]);
;             }
;     }
; __device__ __forceinline__ u32x4 pack8(f32x4 a, f32x4 b) { u32x4 w; w.x = pk2(a[0], a[1]); w.y = pk2(a[2], a[3]); w.z = pk2(b[0], b[1]); w.w = pk2(b[2], b[3]); return w; }
; __device__ __forceinline__ void unpack8(u32x4 w, f32x4& a, f32x4& b) { a = (f32x4){bf_lo(w.x), bf_hi(w.x), bf_lo(w.y), bf_hi(w.y)}; b = (f32x4){bf_lo(w.z), bf_hi(w.z), bf_lo(w.w), bf_hi(w.w)}; }
;     __device__ __forceinline__ void operator()(const Unit& u, int row, int col, f32x4 v0, f32x4 v1) const {
;         const int pn = u.pn;
;         if (pn < 2) {
;             const int c = pn * 256 + col, g = c >> 4, p = c & 15;
;             *(GAS u32x4*)(Ap + ((size_t)(g * 2048 + (row >> 4)) * 512 + (row & 15) * 16 + p)) = pack8(v0, v1);
.LBB0_186:
	s_cmp_lt_u32 s76, 2
	s_cbranch_scc1 .Lfp_cls0
	s_cmp_lt_u32 s76, 8
	s_cbranch_scc1 .Lfp_cls1
	s_cmp_lt_u32 s76, 10
	s_cbranch_scc1 .Lfp_cls2
	s_cmp_lt_u32 s76, 22
	s_cbranch_scc1 .Lfp_cls3
	s_branch .Lfp_cls4
.Lfp_cls0:
	s_mov_b32 s98, 0xbfb8aa3b
	s_mov_b32 s100, 1.0
	s_lshl_b32 s57, s6, 8
	s_add_i32 s57, s57, s85
	s_lshl_b32 s68, s76, 8
	s_add_i32 s38, s68, 0xffffea00
	v_or_b32_e32 v150, s57, v162
	s_and_b32 s8, s76, 14
	v_ashrrev_i32_e32 v151, 31, v150
	v_lshlrev_b64 v[152:153], 10, v[150:151]
	v_mad_i64_i32 v[150:151], s[8:9], v150, s10, 0
	s_lshl_b32 s21, s76, 15
	v_add_u32_e32 v154, s21, v164
	s_ashr_i32 s59, s57, 4
	v_and_b32_e32 v154, 0xfffff800, v154
	v_cvt_pk_bf16_f32 v120, v120, v121
	v_cvt_pk_bf16_f32 v121, v122, v123
	v_cvt_pk_bf16_f32 v122, v124, v125
	v_add_u32_e32 v124, s59, v154
	v_ashrrev_i32_e32 v125, 31, v124
	v_lshlrev_b64 v[124:125], 10, v[124:125]
	v_cvt_pk_bf16_f32 v123, v126, v127
	v_lshl_add_u64 v[124:125], v[140:141], 0, v[124:125]
	global_store_dwordx4 v[124:125], v[120:123], off
	s_nop 1
	v_add_u32_e32 v120, s21, v165
	v_and_b32_e32 v124, 0xfffff800, v120
	v_cvt_pk_bf16_f32 v116, v116, v117
	v_cvt_pk_bf16_f32 v117, v118, v119
	v_cvt_pk_bf16_f32 v118, v112, v113
	v_add_u32_e32 v112, s59, v124
	v_ashrrev_i32_e32 v113, 31, v112
	v_lshlrev_b64 v[112:113], 10, v[112:113]
	v_cvt_pk_bf16_f32 v119, v114, v115
	v_lshl_add_u64 v[112:113], v[140:141], 0, v[112:113]
	global_store_dwordx4 v[112:113], v[116:119], off
	s_or_b32 s21, s57, 16
	v_or_b32_e32 v112, s21, v162
	v_ashrrev_i32_e32 v113, 31, v112
	v_lshlrev_b64 v[114:115], 10, v[112:113]
	v_mad_i64_i32 v[112:113], s[74:75], v112, s10, 0
	s_ashr_i32 s21, s21, 4
	v_cvt_pk_bf16_f32 v108, v108, v109
	v_cvt_pk_bf16_f32 v109, v110, v111
	v_cvt_pk_bf16_f32 v110, v104, v105
	v_add_u32_e32 v104, s21, v154
	v_ashrrev_i32_e32 v105, 31, v104
	v_lshlrev_b64 v[104:105], 10, v[104:105]
	v_cvt_pk_bf16_f32 v111, v106, v107
	v_lshl_add_u64 v[104:105], v[140:141], 0, v[104:105]
	global_store_dwordx4 v[104:105], v[108:111], off
	v_cvt_pk_bf16_f32 v100, v100, v101
	v_cvt_pk_bf16_f32 v101, v102, v103
	v_cvt_pk_bf16_f32 v102, v96, v97
	v_add_u32_e32 v96, s21, v124
	v_ashrrev_i32_e32 v97, 31, v96
	v_lshlrev_b64 v[96:97], 10, v[96:97]
	v_cvt_pk_bf16_f32 v103, v98, v99
	v_lshl_add_u64 v[96:97], v[140:141], 0, v[96:97]
	global_store_dwordx4 v[96:97], v[100:103], off
	s_or_b32 s21, s57, 32
	v_or_b32_e32 v96, s21, v162
	v_ashrrev_i32_e32 v97, 31, v96
	v_lshlrev_b64 v[98:99], 10, v[96:97]
	v_mad_i64_i32 v[96:97], s[74:75], v96, s10, 0
	s_ashr_i32 s21, s21, 4
	v_cvt_pk_bf16_f32 v92, v92, v93
	v_cvt_pk_bf16_f32 v93, v94, v95
	v_cvt_pk_bf16_f32 v94, v88, v89
	v_add_u32_e32 v88, s21, v154
	v_ashrrev_i32_e32 v89, 31, v88
	v_lshlrev_b64 v[88:89], 10, v[88:89]
	v_cvt_pk_bf16_f32 v95, v90, v91
	v_lshl_add_u64 v[88:89], v[140:141], 0, v[88:89]
	global_store_dwordx4 v[88:89], v[92:95], off
	v_cvt_pk_bf16_f32 v84, v84, v85
	v_cvt_pk_bf16_f32 v85, v86, v87
	v_cvt_pk_bf16_f32 v86, v80, v81
	v_add_u32_e32 v80, s21, v124
	v_ashrrev_i32_e32 v81, 31, v80
	v_lshlrev_b64 v[80:81], 10, v[80:81]
	v_cvt_pk_bf16_f32 v87, v82, v83
	v_lshl_add_u64 v[80:81], v[140:141], 0, v[80:81]
	global_store_dwordx4 v[80:81], v[84:87], off
	s_or_b32 s21, s57, 48
	v_or_b32_e32 v80, s21, v162
	v_ashrrev_i32_e32 v81, 31, v80
	v_lshlrev_b64 v[82:83], 10, v[80:81]
	v_mad_i64_i32 v[80:81], s[74:75], v80, s10, 0
	s_ashr_i32 s21, s21, 4
	v_cvt_pk_bf16_f32 v76, v76, v77
	v_cvt_pk_bf16_f32 v77, v78, v79
	v_cvt_pk_bf16_f32 v78, v72, v73
	v_add_u32_e32 v72, s21, v154
	v_ashrrev_i32_e32 v73, 31, v72
	v_lshlrev_b64 v[72:73], 10, v[72:73]
	v_cvt_pk_bf16_f32 v79, v74, v75
	v_lshl_add_u64 v[72:73], v[140:141], 0, v[72:73]
	global_store_dwordx4 v[72:73], v[76:79], off
	v_cvt_pk_bf16_f32 v68, v68, v69
	v_cvt_pk_bf16_f32 v69, v70, v71
	v_cvt_pk_bf16_f32 v70, v64, v65
	v_add_u32_e32 v64, s21, v124
	v_ashrrev_i32_e32 v65, 31, v64
	v_lshlrev_b64 v[64:65], 10, v[64:65]
	v_cvt_pk_bf16_f32 v71, v66, v67
	v_lshl_add_u64 v[64:65], v[140:141], 0, v[64:65]
	global_store_dwordx4 v[64:65], v[68:71], off
	s_add_i32 s21, s57, 0x80
	v_or_b32_e32 v64, s21, v162
	v_ashrrev_i32_e32 v65, 31, v64
	v_lshlrev_b64 v[66:67], 10, v[64:65]
	v_mad_i64_i32 v[64:65], s[74:75], v64, s10, 0
	s_ashr_i32 s21, s21, 4
	v_cvt_pk_bf16_f32 v60, v60, v61
	v_cvt_pk_bf16_f32 v61, v62, v63
	v_cvt_pk_bf16_f32 v62, v56, v57
	v_add_u32_e32 v56, s21, v154
	v_ashrrev_i32_e32 v57, 31, v56
	v_lshlrev_b64 v[56:57], 10, v[56:57]
	v_cvt_pk_bf16_f32 v63, v58, v59
	v_lshl_add_u64 v[56:57], v[140:141], 0, v[56:57]
	global_store_dwordx4 v[56:57], v[60:63], off
	v_cvt_pk_bf16_f32 v52, v52, v53
	v_cvt_pk_bf16_f32 v53, v54, v55
	v_cvt_pk_bf16_f32 v54, v48, v49
	v_add_u32_e32 v48, s21, v124
	v_ashrrev_i32_e32 v49, 31, v48
	v_lshlrev_b64 v[48:49], 10, v[48:49]
	v_cvt_pk_bf16_f32 v55, v50, v51
	v_lshl_add_u64 v[48:49], v[140:141], 0, v[48:49]
	global_store_dwordx4 v[48:49], v[52:55], off
	s_add_i32 s21, s57, 0x90
	v_or_b32_e32 v48, s21, v162
	v_ashrrev_i32_e32 v49, 31, v48
	v_lshlrev_b64 v[50:51], 10, v[48:49]
	v_mad_i64_i32 v[48:49], s[74:75], v48, s10, 0
	s_ashr_i32 s21, s21, 4
	v_cvt_pk_bf16_f32 v44, v44, v45
	v_cvt_pk_bf16_f32 v45, v46, v47
	v_cvt_pk_bf16_f32 v46, v40, v41
	v_add_u32_e32 v40, s21, v154
	v_ashrrev_i32_e32 v41, 31, v40
	v_lshlrev_b64 v[40:41], 10, v[40:41]
	v_cvt_pk_bf16_f32 v47, v42, v43
	v_lshl_add_u64 v[40:41], v[140:141], 0, v[40:41]
	global_store_dwordx4 v[40:41], v[44:47], off
	v_cvt_pk_bf16_f32 v36, v36, v37
	v_cvt_pk_bf16_f32 v37, v38, v39
	v_cvt_pk_bf16_f32 v38, v32, v33
	v_add_u32_e32 v32, s21, v124
	v_ashrrev_i32_e32 v33, 31, v32
	v_lshlrev_b64 v[32:33], 10, v[32:33]
; #define GAS __attribute__((address_space(1)))
; __device__ __forceinline__ float sigmoidf_(float x) { return frcp(1.f + fexp2(-x * LOG2E)); }
; __device__ __forceinline__ float siluf_(float x) { return x * sigmoidf_(x); }
; __device__ __forceinline__ u32x4 pack8(f32x4 a, f32x4 b) { u32x4 w; w.x = pk2(a[0], a[1]); w.y = pk2(a[2], a[3]); w.z = pk2(b[0], b[1]); w.w = pk2(b[2], b[3]); return w; }
;     __device__ __forceinline__ void operator()(const Unit& u, int row, int col, f32x4 v0, f32x4 v1) const {
;     ...
;             const int pc = pn * 256 - 512 + col;
;             if (pn >= 10) {
;                 const f32x4 b0 = *(const GAS f32x4*)(b_gate + pc - PC_GATE), b1 = *(const GAS f32x4*)(b_gate + pc - PC_GATE + 4);
; #pragma unroll
;                 for (int i = 0; i < 4; ++i) { v0[i] = sigmoidf_(v0[i] + b0[i]); v1[i] = sigmoidf_(v1[i] + b1[i]); }
;             } else if (pn == 8 || pn == 9) {
;                 const float sc = 0.08838834764831845f * LOG2E;
;                 v0 = v0 * sc; v1 = v1 * sc;
;             } else {
; #pragma unroll
;                 for (int i = 0; i < 4; ++i) { v0[i] = siluf_(v0[i]); v1[i] = siluf_(v1[i]); }
;             }
;             __builtin_nontemporal_store(pack8(v0, v1), (GAS u32x4*)(P + (size_t)row * PW + pc));
	v_cvt_pk_bf16_f32 v39, v34, v35
	v_lshl_add_u64 v[32:33], v[140:141], 0, v[32:33]
	global_store_dwordx4 v[32:33], v[36:39], off
	s_add_i32 s21, s57, 0xa0
	v_or_b32_e32 v32, s21, v162
	v_ashrrev_i32_e32 v33, 31, v32
	v_lshlrev_b64 v[34:35], 10, v[32:33]
	v_mad_i64_i32 v[32:33], s[74:75], v32, s10, 0
	s_ashr_i32 s21, s21, 4
	v_cvt_pk_bf16_f32 v28, v28, v29
	v_cvt_pk_bf16_f32 v29, v30, v31
	v_cvt_pk_bf16_f32 v30, v24, v25
	v_add_u32_e32 v24, s21, v154
	v_ashrrev_i32_e32 v25, 31, v24
	v_lshlrev_b64 v[24:25], 10, v[24:25]
	v_cvt_pk_bf16_f32 v31, v26, v27
	v_lshl_add_u64 v[24:25], v[140:141], 0, v[24:25]
	global_store_dwordx4 v[24:25], v[28:31], off
	v_cvt_pk_bf16_f32 v20, v20, v21
	v_cvt_pk_bf16_f32 v21, v22, v23
	v_cvt_pk_bf16_f32 v22, v16, v17
	v_add_u32_e32 v16, s21, v124
	v_ashrrev_i32_e32 v17, 31, v16
	v_lshlrev_b64 v[16:17], 10, v[16:17]
	v_cvt_pk_bf16_f32 v23, v18, v19
	v_lshl_add_u64 v[16:17], v[140:141], 0, v[16:17]
	global_store_dwordx4 v[16:17], v[20:23], off
	s_addk_i32 s57, 0xb0
	v_or_b32_e32 v16, s57, v162
	v_ashrrev_i32_e32 v17, 31, v16
	v_lshlrev_b64 v[18:19], 10, v[16:17]
	v_mad_i64_i32 v[16:17], s[74:75], v16, s10, 0
	s_ashr_i32 s21, s57, 4
	v_cvt_pk_bf16_f32 v12, v12, v13
	v_cvt_pk_bf16_f32 v13, v14, v15
	v_cvt_pk_bf16_f32 v14, v8, v9
	v_add_u32_e32 v8, s21, v154
	v_ashrrev_i32_e32 v9, 31, v8
	v_lshlrev_b64 v[8:9], 10, v[8:9]
	v_cvt_pk_bf16_f32 v15, v10, v11
	v_lshl_add_u64 v[8:9], v[140:141], 0, v[8:9]
	global_store_dwordx4 v[8:9], v[12:15], off
	v_cvt_pk_bf16_f32 v4, v4, v5
	v_cvt_pk_bf16_f32 v5, v6, v7
	v_cvt_pk_bf16_f32 v6, v0, v1
	v_add_u32_e32 v0, s21, v124
	v_ashrrev_i32_e32 v1, 31, v0
	v_lshlrev_b64 v[0:1], 10, v[0:1]
	v_cvt_pk_bf16_f32 v7, v2, v3
	v_lshl_add_u64 v[0:1], v[140:141], 0, v[0:1]
	global_store_dwordx4 v[0:1], v[4:7], off
	s_andn2_b64 vcc, exec, s[4:5]
	s_mov_b64 s[4:5], -1
	s_cbranch_vccnz .LBB0_178
	s_andn2_b64 vcc, exec, s[40:41]
	s_cbranch_vccnz .LBB0_177
	s_barrier
	s_branch .LBB0_177
.Lfp_cls1:
	s_mov_b32 s98, 0xbfb8aa3b
	s_mov_b32 s100, 1.0
	s_lshl_b32 s57, s6, 8
	s_add_i32 s57, s57, s85
	s_lshl_b32 s68, s76, 8
	s_add_i32 s38, s68, 0xffffea00
	v_or_b32_e32 v150, s57, v162
	s_and_b32 s8, s76, 14
	v_ashrrev_i32_e32 v151, 31, v150
	v_lshlrev_b64 v[152:153], 10, v[150:151]
	v_mad_i64_i32 v[150:151], s[8:9], v150, s10, 0
	v_pk_mul_f32 v[212:213], v[120:121], s[98:99] op_sel_hi:[1,0]
	v_pk_mul_f32 v[214:215], v[122:123], s[98:99] op_sel_hi:[1,0]
	v_pk_mul_f32 v[216:217], v[126:127], s[98:99] op_sel_hi:[1,0]
	v_pk_mul_f32 v[218:219], v[124:125], s[98:99] op_sel_hi:[1,0]
	v_exp_f32_e32 v212, v212
	v_exp_f32_e32 v213, v213
	v_exp_f32_e32 v214, v214
	v_exp_f32_e32 v215, v215
	v_exp_f32_e32 v216, v216
	v_exp_f32_e32 v217, v217
	v_exp_f32_e32 v218, v218
	v_exp_f32_e32 v219, v219
	v_pk_add_f32 v[212:213], v[212:213], s[100:101] op_sel_hi:[1,0]
	v_pk_add_f32 v[214:215], v[214:215], s[100:101] op_sel_hi:[1,0]
	v_pk_add_f32 v[216:217], v[216:217], s[100:101] op_sel_hi:[1,0]
	v_pk_add_f32 v[218:219], v[218:219], s[100:101] op_sel_hi:[1,0]
	v_rcp_f32_e32 v212, v212
	v_rcp_f32_e32 v213, v213
	v_rcp_f32_e32 v214, v214
	v_rcp_f32_e32 v215, v215
	v_rcp_f32_e32 v216, v216
	v_rcp_f32_e32 v217, v217
	v_rcp_f32_e32 v218, v218
	v_rcp_f32_e32 v219, v219
	v_pk_mul_f32 v[156:157], v[120:121], v[212:213]
	v_pk_mul_f32 v[154:155], v[122:123], v[214:215]
	v_pk_mul_f32 v[158:159], v[126:127], v[216:217]
	v_pk_mul_f32 v[160:161], v[124:125], v[218:219]
	s_ashr_i32 s69, s68, 31
	v_cvt_pk_bf16_f32 v170, v156, v157
	v_cvt_pk_bf16_f32 v171, v154, v155
	v_lshl_add_u64 v[154:155], s[42:43], 0, v[150:151]
	v_lshl_add_u64 v[156:157], s[68:69], 0, v[136:137]
	v_cvt_pk_bf16_f32 v172, v160, v161
	v_cvt_pk_bf16_f32 v173, v158, v159
	v_lshl_add_u64 v[154:155], v[156:157], 1, v[154:155]
	global_store_dwordx4 v[154:155], v[170:173], off offset:-1024 nt
	s_lshl_b32 s21, s76, 15
	v_add_u32_e32 v154, s21, v164
	s_ashr_i32 s59, s57, 4
	v_and_b32_e32 v154, 0xfffff800, v154
	s_nop 1
	v_pk_mul_f32 v[212:213], v[116:117], s[98:99] op_sel_hi:[1,0]
	v_pk_mul_f32 v[214:215], v[118:119], s[98:99] op_sel_hi:[1,0]
	v_pk_mul_f32 v[216:217], v[114:115], s[98:99] op_sel_hi:[1,0]
	v_pk_mul_f32 v[218:219], v[112:113], s[98:99] op_sel_hi:[1,0]
	v_exp_f32_e32 v212, v212
	v_exp_f32_e32 v213, v213
	v_exp_f32_e32 v214, v214
	v_exp_f32_e32 v215, v215
	v_exp_f32_e32 v216, v216
	v_exp_f32_e32 v217, v217
	v_exp_f32_e32 v218, v218
	v_exp_f32_e32 v219, v219
	v_pk_add_f32 v[212:213], v[212:213], s[100:101] op_sel_hi:[1,0]
	v_pk_add_f32 v[214:215], v[214:215], s[100:101] op_sel_hi:[1,0]
	v_pk_add_f32 v[216:217], v[216:217], s[100:101] op_sel_hi:[1,0]
	v_pk_add_f32 v[218:219], v[218:219], s[100:101] op_sel_hi:[1,0]
	v_rcp_f32_e32 v212, v212
	v_rcp_f32_e32 v213, v213
	v_rcp_f32_e32 v214, v214
	v_rcp_f32_e32 v215, v215
	v_rcp_f32_e32 v216, v216
	v_rcp_f32_e32 v217, v217
	v_rcp_f32_e32 v218, v218
	v_rcp_f32_e32 v219, v219
	v_pk_mul_f32 v[122:123], v[116:117], v[212:213]
	v_pk_mul_f32 v[120:121], v[118:119], v[214:215]
	v_pk_mul_f32 v[124:125], v[114:115], v[216:217]
	v_pk_mul_f32 v[126:127], v[112:113], v[218:219]
	s_ashr_i32 s69, s68, 31
	v_cvt_pk_bf16_f32 v156, v122, v123
	v_cvt_pk_bf16_f32 v157, v120, v121
	v_lshl_add_u64 v[120:121], s[42:43], 0, v[150:151]
	v_lshl_add_u64 v[122:123], s[68:69], 0, v[138:139]
	v_cvt_pk_bf16_f32 v158, v126, v127
	v_cvt_pk_bf16_f32 v159, v124, v125
	v_lshl_add_u64 v[120:121], v[122:123], 1, v[120:121]
	global_store_dwordx4 v[120:121], v[156:159], off offset:-1024 nt
	v_add_u32_e32 v120, s21, v165
	v_and_b32_e32 v124, 0xfffff800, v120
	s_or_b32 s21, s57, 16
	v_or_b32_e32 v112, s21, v162
	v_ashrrev_i32_e32 v113, 31, v112
	v_lshlrev_b64 v[114:115], 10, v[112:113]
; #define GAS __attribute__((address_space(1)))
; __device__ __forceinline__ float siluf_(float x) { return x * sigmoidf_(x); }
; __device__ __forceinline__ u32x4 pack8(f32x4 a, f32x4 b) { u32x4 w; w.x = pk2(a[0], a[1]); w.y = pk2(a[2], a[3]); w.z = pk2(b[0], b[1]); w.w = pk2(b[2], b[3]); return w; }
;     __device__ __forceinline__ void operator()(const Unit& u, int row, int col, f32x4 v0, f32x4 v1) const {
;     ...
; #pragma unroll
;                 for (int i = 0; i < 4; ++i) { v0[i] = siluf_(v0[i]); v1[i] = siluf_(v1[i]); }
;             }
;             __builtin_nontemporal_store(pack8(v0, v1), (GAS u32x4*)(P + (size_t)row * PW + pc));
	v_mad_i64_i32 v[112:113], s[74:75], v112, s10, 0
	v_pk_mul_f32 v[212:213], v[108:109], s[98:99] op_sel_hi:[1,0]
	v_pk_mul_f32 v[214:215], v[110:111], s[98:99] op_sel_hi:[1,0]
	v_pk_mul_f32 v[216:217], v[106:107], s[98:99] op_sel_hi:[1,0]
	v_pk_mul_f32 v[218:219], v[104:105], s[98:99] op_sel_hi:[1,0]
	v_exp_f32_e32 v212, v212
	v_exp_f32_e32 v213, v213
	v_exp_f32_e32 v214, v214
	v_exp_f32_e32 v215, v215
	v_exp_f32_e32 v216, v216
	v_exp_f32_e32 v217, v217
	v_exp_f32_e32 v218, v218
	v_exp_f32_e32 v219, v219
	v_pk_add_f32 v[212:213], v[212:213], s[100:101] op_sel_hi:[1,0]
	v_pk_add_f32 v[214:215], v[214:215], s[100:101] op_sel_hi:[1,0]
	v_pk_add_f32 v[216:217], v[216:217], s[100:101] op_sel_hi:[1,0]
	v_pk_add_f32 v[218:219], v[218:219], s[100:101] op_sel_hi:[1,0]
	v_rcp_f32_e32 v212, v212
	v_rcp_f32_e32 v213, v213
	v_rcp_f32_e32 v214, v214
	v_rcp_f32_e32 v215, v215
	v_rcp_f32_e32 v216, v216
	v_rcp_f32_e32 v217, v217
	v_rcp_f32_e32 v218, v218
	v_rcp_f32_e32 v219, v219
	v_pk_mul_f32 v[118:119], v[108:109], v[212:213]
	v_pk_mul_f32 v[116:117], v[110:111], v[214:215]
	v_pk_mul_f32 v[120:121], v[106:107], v[216:217]
	v_pk_mul_f32 v[122:123], v[104:105], v[218:219]
	s_ashr_i32 s69, s68, 31
	v_cvt_pk_bf16_f32 v150, v118, v119
	v_cvt_pk_bf16_f32 v151, v116, v117
	v_lshl_add_u64 v[116:117], s[42:43], 0, v[112:113]
	v_lshl_add_u64 v[118:119], s[68:69], 0, v[136:137]
	v_cvt_pk_bf16_f32 v152, v122, v123
	v_cvt_pk_bf16_f32 v153, v120, v121
	v_lshl_add_u64 v[116:117], v[118:119], 1, v[116:117]
	global_store_dwordx4 v[116:117], v[150:153], off offset:-1024 nt
	s_ashr_i32 s21, s21, 4
	v_pk_mul_f32 v[212:213], v[100:101], s[98:99] op_sel_hi:[1,0]
	v_pk_mul_f32 v[214:215], v[102:103], s[98:99] op_sel_hi:[1,0]
	v_pk_mul_f32 v[216:217], v[98:99], s[98:99] op_sel_hi:[1,0]
	v_pk_mul_f32 v[218:219], v[96:97], s[98:99] op_sel_hi:[1,0]
	v_exp_f32_e32 v212, v212
	v_exp_f32_e32 v213, v213
	v_exp_f32_e32 v214, v214
	v_exp_f32_e32 v215, v215
	v_exp_f32_e32 v216, v216
	v_exp_f32_e32 v217, v217
	v_exp_f32_e32 v218, v218
	v_exp_f32_e32 v219, v219
	v_pk_add_f32 v[212:213], v[212:213], s[100:101] op_sel_hi:[1,0]
	v_pk_add_f32 v[214:215], v[214:215], s[100:101] op_sel_hi:[1,0]
	v_pk_add_f32 v[216:217], v[216:217], s[100:101] op_sel_hi:[1,0]
	v_pk_add_f32 v[218:219], v[218:219], s[100:101] op_sel_hi:[1,0]
	v_rcp_f32_e32 v212, v212
	v_rcp_f32_e32 v213, v213
	v_rcp_f32_e32 v214, v214
	v_rcp_f32_e32 v215, v215
	v_rcp_f32_e32 v216, v216
	v_rcp_f32_e32 v217, v217
	v_rcp_f32_e32 v218, v218
	v_rcp_f32_e32 v219, v219
	v_pk_mul_f32 v[106:107], v[100:101], v[212:213]
	v_pk_mul_f32 v[104:105], v[102:103], v[214:215]
	v_pk_mul_f32 v[108:109], v[98:99], v[216:217]
	v_pk_mul_f32 v[110:111], v[96:97], v[218:219]
	s_ashr_i32 s69, s68, 31
	v_cvt_pk_bf16_f32 v114, v106, v107
	v_cvt_pk_bf16_f32 v115, v104, v105
	v_lshl_add_u64 v[104:105], s[42:43], 0, v[112:113]
	v_lshl_add_u64 v[106:107], s[68:69], 0, v[138:139]
	v_cvt_pk_bf16_f32 v116, v110, v111
	v_cvt_pk_bf16_f32 v117, v108, v109
	v_lshl_add_u64 v[104:105], v[106:107], 1, v[104:105]
	global_store_dwordx4 v[104:105], v[114:117], off offset:-1024 nt
	s_or_b32 s21, s57, 32
	v_or_b32_e32 v96, s21, v162
	v_ashrrev_i32_e32 v97, 31, v96
	v_lshlrev_b64 v[98:99], 10, v[96:97]
	v_mad_i64_i32 v[96:97], s[74:75], v96, s10, 0
	v_pk_mul_f32 v[212:213], v[92:93], s[98:99] op_sel_hi:[1,0]
	v_pk_mul_f32 v[214:215], v[94:95], s[98:99] op_sel_hi:[1,0]
	v_pk_mul_f32 v[216:217], v[90:91], s[98:99] op_sel_hi:[1,0]
	v_pk_mul_f32 v[218:219], v[88:89], s[98:99] op_sel_hi:[1,0]
	v_exp_f32_e32 v212, v212
	v_exp_f32_e32 v213, v213
	v_exp_f32_e32 v214, v214
	v_exp_f32_e32 v215, v215
	v_exp_f32_e32 v216, v216
	v_exp_f32_e32 v217, v217
	v_exp_f32_e32 v218, v218
	v_exp_f32_e32 v219, v219
	v_pk_add_f32 v[212:213], v[212:213], s[100:101] op_sel_hi:[1,0]
	v_pk_add_f32 v[214:215], v[214:215], s[100:101] op_sel_hi:[1,0]
	v_pk_add_f32 v[216:217], v[216:217], s[100:101] op_sel_hi:[1,0]
	v_pk_add_f32 v[218:219], v[218:219], s[100:101] op_sel_hi:[1,0]
	v_rcp_f32_e32 v212, v212
	v_rcp_f32_e32 v213, v213
	v_rcp_f32_e32 v214, v214
	v_rcp_f32_e32 v215, v215
	v_rcp_f32_e32 v216, v216
	v_rcp_f32_e32 v217, v217
	v_rcp_f32_e32 v218, v218
	v_rcp_f32_e32 v219, v219
	v_pk_mul_f32 v[102:103], v[92:93], v[212:213]
	v_pk_mul_f32 v[100:101], v[94:95], v[214:215]
	v_pk_mul_f32 v[104:105], v[90:91], v[216:217]
	v_pk_mul_f32 v[106:107], v[88:89], v[218:219]
	s_ashr_i32 s69, s68, 31
	v_cvt_pk_bf16_f32 v108, v102, v103
	v_cvt_pk_bf16_f32 v109, v100, v101
	v_lshl_add_u64 v[100:101], s[42:43], 0, v[96:97]
	v_lshl_add_u64 v[102:103], s[68:69], 0, v[136:137]
	v_cvt_pk_bf16_f32 v110, v106, v107
	v_cvt_pk_bf16_f32 v111, v104, v105
	v_lshl_add_u64 v[100:101], v[102:103], 1, v[100:101]
	global_store_dwordx4 v[100:101], v[108:111], off offset:-1024 nt
	s_ashr_i32 s21, s21, 4
	v_pk_mul_f32 v[212:213], v[84:85], s[98:99] op_sel_hi:[1,0]
	v_pk_mul_f32 v[214:215], v[86:87], s[98:99] op_sel_hi:[1,0]
	v_pk_mul_f32 v[216:217], v[82:83], s[98:99] op_sel_hi:[1,0]
	v_pk_mul_f32 v[218:219], v[80:81], s[98:99] op_sel_hi:[1,0]
	v_exp_f32_e32 v212, v212
	v_exp_f32_e32 v213, v213
	v_exp_f32_e32 v214, v214
	v_exp_f32_e32 v215, v215
	v_exp_f32_e32 v216, v216
	v_exp_f32_e32 v217, v217
	v_exp_f32_e32 v218, v218
	v_exp_f32_e32 v219, v219
	v_pk_add_f32 v[212:213], v[212:213], s[100:101] op_sel_hi:[1,0]
	v_pk_add_f32 v[214:215], v[214:215], s[100:101] op_sel_hi:[1,0]
	v_pk_add_f32 v[216:217], v[216:217], s[100:101] op_sel_hi:[1,0]
	v_pk_add_f32 v[218:219], v[218:219], s[100:101] op_sel_hi:[1,0]
	v_rcp_f32_e32 v212, v212
	v_rcp_f32_e32 v213, v213
	v_rcp_f32_e32 v214, v214
	v_rcp_f32_e32 v215, v215
	v_rcp_f32_e32 v216, v216
; #define GAS __attribute__((address_space(1)))
; __device__ __forceinline__ float siluf_(float x) { return x * sigmoidf_(x); }
; __device__ __forceinline__ u32x4 pack8(f32x4 a, f32x4 b) { u32x4 w; w.x = pk2(a[0], a[1]); w.y = pk2(a[2], a[3]); w.z = pk2(b[0], b[1]); w.w = pk2(b[2], b[3]); return w; }
;     __device__ __forceinline__ void operator()(const Unit& u, int row, int col, f32x4 v0, f32x4 v1) const {
;     ...
; #pragma unroll
;                 for (int i = 0; i < 4; ++i) { v0[i] = siluf_(v0[i]); v1[i] = siluf_(v1[i]); }
;             }
;             __builtin_nontemporal_store(pack8(v0, v1), (GAS u32x4*)(P + (size_t)row * PW + pc));
	v_rcp_f32_e32 v217, v217
	v_rcp_f32_e32 v218, v218
	v_rcp_f32_e32 v219, v219
	v_pk_mul_f32 v[90:91], v[84:85], v[212:213]
	v_pk_mul_f32 v[88:89], v[86:87], v[214:215]
	v_pk_mul_f32 v[92:93], v[82:83], v[216:217]
	v_pk_mul_f32 v[94:95], v[80:81], v[218:219]
	s_ashr_i32 s69, s68, 31
	v_cvt_pk_bf16_f32 v98, v90, v91
	v_cvt_pk_bf16_f32 v99, v88, v89
	v_lshl_add_u64 v[88:89], s[42:43], 0, v[96:97]
	v_lshl_add_u64 v[90:91], s[68:69], 0, v[138:139]
	v_cvt_pk_bf16_f32 v100, v94, v95
	v_cvt_pk_bf16_f32 v101, v92, v93
	v_lshl_add_u64 v[88:89], v[90:91], 1, v[88:89]
	global_store_dwordx4 v[88:89], v[98:101], off offset:-1024 nt
	s_or_b32 s21, s57, 48
	v_or_b32_e32 v80, s21, v162
	v_ashrrev_i32_e32 v81, 31, v80
	v_lshlrev_b64 v[82:83], 10, v[80:81]
	v_mad_i64_i32 v[80:81], s[74:75], v80, s10, 0
	v_pk_mul_f32 v[212:213], v[76:77], s[98:99] op_sel_hi:[1,0]
	v_pk_mul_f32 v[214:215], v[78:79], s[98:99] op_sel_hi:[1,0]
	v_pk_mul_f32 v[216:217], v[74:75], s[98:99] op_sel_hi:[1,0]
	v_pk_mul_f32 v[218:219], v[72:73], s[98:99] op_sel_hi:[1,0]
	v_exp_f32_e32 v212, v212
	v_exp_f32_e32 v213, v213
	v_exp_f32_e32 v214, v214
	v_exp_f32_e32 v215, v215
	v_exp_f32_e32 v216, v216
	v_exp_f32_e32 v217, v217
	v_exp_f32_e32 v218, v218
	v_exp_f32_e32 v219, v219
	v_pk_add_f32 v[212:213], v[212:213], s[100:101] op_sel_hi:[1,0]
	v_pk_add_f32 v[214:215], v[214:215], s[100:101] op_sel_hi:[1,0]
	v_pk_add_f32 v[216:217], v[216:217], s[100:101] op_sel_hi:[1,0]
	v_pk_add_f32 v[218:219], v[218:219], s[100:101] op_sel_hi:[1,0]
	v_rcp_f32_e32 v212, v212
	v_rcp_f32_e32 v213, v213
	v_rcp_f32_e32 v214, v214
	v_rcp_f32_e32 v215, v215
	v_rcp_f32_e32 v216, v216
	v_rcp_f32_e32 v217, v217
	v_rcp_f32_e32 v218, v218
	v_rcp_f32_e32 v219, v219
	v_pk_mul_f32 v[86:87], v[76:77], v[212:213]
	v_pk_mul_f32 v[84:85], v[78:79], v[214:215]
	v_pk_mul_f32 v[88:89], v[74:75], v[216:217]
	v_pk_mul_f32 v[90:91], v[72:73], v[218:219]
	s_ashr_i32 s69, s68, 31
	v_cvt_pk_bf16_f32 v92, v86, v87
	v_cvt_pk_bf16_f32 v93, v84, v85
	v_lshl_add_u64 v[84:85], s[42:43], 0, v[80:81]
	v_lshl_add_u64 v[86:87], s[68:69], 0, v[136:137]
	v_cvt_pk_bf16_f32 v94, v90, v91
	v_cvt_pk_bf16_f32 v95, v88, v89
	v_lshl_add_u64 v[84:85], v[86:87], 1, v[84:85]
	global_store_dwordx4 v[84:85], v[92:95], off offset:-1024 nt
	s_ashr_i32 s21, s21, 4
	v_pk_mul_f32 v[212:213], v[68:69], s[98:99] op_sel_hi:[1,0]
	v_pk_mul_f32 v[214:215], v[70:71], s[98:99] op_sel_hi:[1,0]
	v_pk_mul_f32 v[216:217], v[66:67], s[98:99] op_sel_hi:[1,0]
	v_pk_mul_f32 v[218:219], v[64:65], s[98:99] op_sel_hi:[1,0]
	v_exp_f32_e32 v212, v212
	v_exp_f32_e32 v213, v213
	v_exp_f32_e32 v214, v214
	v_exp_f32_e32 v215, v215
	v_exp_f32_e32 v216, v216
	v_exp_f32_e32 v217, v217
	v_exp_f32_e32 v218, v218
	v_exp_f32_e32 v219, v219
	v_pk_add_f32 v[212:213], v[212:213], s[100:101] op_sel_hi:[1,0]
	v_pk_add_f32 v[214:215], v[214:215], s[100:101] op_sel_hi:[1,0]
	v_pk_add_f32 v[216:217], v[216:217], s[100:101] op_sel_hi:[1,0]
	v_pk_add_f32 v[218:219], v[218:219], s[100:101] op_sel_hi:[1,0]
	v_rcp_f32_e32 v212, v212
	v_rcp_f32_e32 v213, v213
	v_rcp_f32_e32 v214, v214
	v_rcp_f32_e32 v215, v215
	v_rcp_f32_e32 v216, v216
	v_rcp_f32_e32 v217, v217
	v_rcp_f32_e32 v218, v218
	v_rcp_f32_e32 v219, v219
	v_pk_mul_f32 v[74:75], v[68:69], v[212:213]
	v_pk_mul_f32 v[72:73], v[70:71], v[214:215]
	v_pk_mul_f32 v[76:77], v[66:67], v[216:217]
	v_pk_mul_f32 v[78:79], v[64:65], v[218:219]
	s_ashr_i32 s69, s68, 31
	v_cvt_pk_bf16_f32 v82, v74, v75
	v_cvt_pk_bf16_f32 v83, v72, v73
	v_lshl_add_u64 v[72:73], s[42:43], 0, v[80:81]
	v_lshl_add_u64 v[74:75], s[68:69], 0, v[138:139]
	v_cvt_pk_bf16_f32 v84, v78, v79
	v_cvt_pk_bf16_f32 v85, v76, v77
	v_lshl_add_u64 v[72:73], v[74:75], 1, v[72:73]
	global_store_dwordx4 v[72:73], v[82:85], off offset:-1024 nt
	s_add_i32 s21, s57, 0x80
	v_or_b32_e32 v64, s21, v162
	v_ashrrev_i32_e32 v65, 31, v64
	v_lshlrev_b64 v[66:67], 10, v[64:65]
	v_mad_i64_i32 v[64:65], s[74:75], v64, s10, 0
	v_pk_mul_f32 v[212:213], v[60:61], s[98:99] op_sel_hi:[1,0]
	v_pk_mul_f32 v[214:215], v[62:63], s[98:99] op_sel_hi:[1,0]
	v_pk_mul_f32 v[216:217], v[58:59], s[98:99] op_sel_hi:[1,0]
	v_pk_mul_f32 v[218:219], v[56:57], s[98:99] op_sel_hi:[1,0]
	v_exp_f32_e32 v212, v212
	v_exp_f32_e32 v213, v213
	v_exp_f32_e32 v214, v214
	v_exp_f32_e32 v215, v215
	v_exp_f32_e32 v216, v216
	v_exp_f32_e32 v217, v217
	v_exp_f32_e32 v218, v218
	v_exp_f32_e32 v219, v219
	v_pk_add_f32 v[212:213], v[212:213], s[100:101] op_sel_hi:[1,0]
	v_pk_add_f32 v[214:215], v[214:215], s[100:101] op_sel_hi:[1,0]
	v_pk_add_f32 v[216:217], v[216:217], s[100:101] op_sel_hi:[1,0]
	v_pk_add_f32 v[218:219], v[218:219], s[100:101] op_sel_hi:[1,0]
	v_rcp_f32_e32 v212, v212
	v_rcp_f32_e32 v213, v213
	v_rcp_f32_e32 v214, v214
	v_rcp_f32_e32 v215, v215
	v_rcp_f32_e32 v216, v216
	v_rcp_f32_e32 v217, v217
	v_rcp_f32_e32 v218, v218
	v_rcp_f32_e32 v219, v219
	v_pk_mul_f32 v[70:71], v[60:61], v[212:213]
	v_pk_mul_f32 v[68:69], v[62:63], v[214:215]
	v_pk_mul_f32 v[72:73], v[58:59], v[216:217]
	v_pk_mul_f32 v[74:75], v[56:57], v[218:219]
	s_ashr_i32 s69, s68, 31
	v_cvt_pk_bf16_f32 v76, v70, v71
	v_cvt_pk_bf16_f32 v77, v68, v69
	v_lshl_add_u64 v[68:69], s[42:43], 0, v[64:65]
	v_lshl_add_u64 v[70:71], s[68:69], 0, v[136:137]
	v_cvt_pk_bf16_f32 v78, v74, v75
	v_cvt_pk_bf16_f32 v79, v72, v73
	v_lshl_add_u64 v[68:69], v[70:71], 1, v[68:69]
	global_store_dwordx4 v[68:69], v[76:79], off offset:-1024 nt
	s_ashr_i32 s21, s21, 4
	v_pk_mul_f32 v[212:213], v[52:53], s[98:99] op_sel_hi:[1,0]
	v_pk_mul_f32 v[214:215], v[54:55], s[98:99] op_sel_hi:[1,0]
	v_pk_mul_f32 v[216:217], v[50:51], s[98:99] op_sel_hi:[1,0]
	v_pk_mul_f32 v[218:219], v[48:49], s[98:99] op_sel_hi:[1,0]
; #define GAS __attribute__((address_space(1)))
; __device__ __forceinline__ float siluf_(float x) { return x * sigmoidf_(x); }
; __device__ __forceinline__ u32x4 pack8(f32x4 a, f32x4 b) { u32x4 w; w.x = pk2(a[0], a[1]); w.y = pk2(a[2], a[3]); w.z = pk2(b[0], b[1]); w.w = pk2(b[2], b[3]); return w; }
;     __device__ __forceinline__ void operator()(const Unit& u, int row, int col, f32x4 v0, f32x4 v1) const {
;     ...
; #pragma unroll
;                 for (int i = 0; i < 4; ++i) { v0[i] = siluf_(v0[i]); v1[i] = siluf_(v1[i]); }
;             }
;             __builtin_nontemporal_store(pack8(v0, v1), (GAS u32x4*)(P + (size_t)row * PW + pc));
	v_exp_f32_e32 v212, v212
	v_exp_f32_e32 v213, v213
	v_exp_f32_e32 v214, v214
	v_exp_f32_e32 v215, v215
	v_exp_f32_e32 v216, v216
	v_exp_f32_e32 v217, v217
	v_exp_f32_e32 v218, v218
	v_exp_f32_e32 v219, v219
	v_pk_add_f32 v[212:213], v[212:213], s[100:101] op_sel_hi:[1,0]
	v_pk_add_f32 v[214:215], v[214:215], s[100:101] op_sel_hi:[1,0]
	v_pk_add_f32 v[216:217], v[216:217], s[100:101] op_sel_hi:[1,0]
	v_pk_add_f32 v[218:219], v[218:219], s[100:101] op_sel_hi:[1,0]
	v_rcp_f32_e32 v212, v212
	v_rcp_f32_e32 v213, v213
	v_rcp_f32_e32 v214, v214
	v_rcp_f32_e32 v215, v215
	v_rcp_f32_e32 v216, v216
	v_rcp_f32_e32 v217, v217
	v_rcp_f32_e32 v218, v218
	v_rcp_f32_e32 v219, v219
	v_pk_mul_f32 v[58:59], v[52:53], v[212:213]
	v_pk_mul_f32 v[56:57], v[54:55], v[214:215]
	v_pk_mul_f32 v[60:61], v[50:51], v[216:217]
	v_pk_mul_f32 v[62:63], v[48:49], v[218:219]
	s_ashr_i32 s69, s68, 31
	v_cvt_pk_bf16_f32 v66, v58, v59
	v_cvt_pk_bf16_f32 v67, v56, v57
	v_lshl_add_u64 v[56:57], s[42:43], 0, v[64:65]
	v_lshl_add_u64 v[58:59], s[68:69], 0, v[138:139]
	v_cvt_pk_bf16_f32 v68, v62, v63
	v_cvt_pk_bf16_f32 v69, v60, v61
	v_lshl_add_u64 v[56:57], v[58:59], 1, v[56:57]
	global_store_dwordx4 v[56:57], v[66:69], off offset:-1024 nt
	s_add_i32 s21, s57, 0x90
	v_or_b32_e32 v48, s21, v162
	v_ashrrev_i32_e32 v49, 31, v48
	v_lshlrev_b64 v[50:51], 10, v[48:49]
	v_mad_i64_i32 v[48:49], s[74:75], v48, s10, 0
	v_pk_mul_f32 v[212:213], v[44:45], s[98:99] op_sel_hi:[1,0]
	v_pk_mul_f32 v[214:215], v[46:47], s[98:99] op_sel_hi:[1,0]
	v_pk_mul_f32 v[216:217], v[42:43], s[98:99] op_sel_hi:[1,0]
	v_pk_mul_f32 v[218:219], v[40:41], s[98:99] op_sel_hi:[1,0]
	v_exp_f32_e32 v212, v212
	v_exp_f32_e32 v213, v213
	v_exp_f32_e32 v214, v214
	v_exp_f32_e32 v215, v215
	v_exp_f32_e32 v216, v216
	v_exp_f32_e32 v217, v217
	v_exp_f32_e32 v218, v218
	v_exp_f32_e32 v219, v219
	v_pk_add_f32 v[212:213], v[212:213], s[100:101] op_sel_hi:[1,0]
	v_pk_add_f32 v[214:215], v[214:215], s[100:101] op_sel_hi:[1,0]
	v_pk_add_f32 v[216:217], v[216:217], s[100:101] op_sel_hi:[1,0]
	v_pk_add_f32 v[218:219], v[218:219], s[100:101] op_sel_hi:[1,0]
	v_rcp_f32_e32 v212, v212
	v_rcp_f32_e32 v213, v213
	v_rcp_f32_e32 v214, v214
	v_rcp_f32_e32 v215, v215
	v_rcp_f32_e32 v216, v216
	v_rcp_f32_e32 v217, v217
	v_rcp_f32_e32 v218, v218
	v_rcp_f32_e32 v219, v219
	v_pk_mul_f32 v[54:55], v[44:45], v[212:213]
	v_pk_mul_f32 v[52:53], v[46:47], v[214:215]
	v_pk_mul_f32 v[56:57], v[42:43], v[216:217]
	v_pk_mul_f32 v[58:59], v[40:41], v[218:219]
	s_ashr_i32 s69, s68, 31
	v_cvt_pk_bf16_f32 v60, v54, v55
	v_cvt_pk_bf16_f32 v61, v52, v53
	v_lshl_add_u64 v[52:53], s[42:43], 0, v[48:49]
	v_lshl_add_u64 v[54:55], s[68:69], 0, v[136:137]
	v_cvt_pk_bf16_f32 v62, v58, v59
	v_cvt_pk_bf16_f32 v63, v56, v57
	v_lshl_add_u64 v[52:53], v[54:55], 1, v[52:53]
	global_store_dwordx4 v[52:53], v[60:63], off offset:-1024 nt
	s_ashr_i32 s21, s21, 4
	v_pk_mul_f32 v[212:213], v[36:37], s[98:99] op_sel_hi:[1,0]
	v_pk_mul_f32 v[214:215], v[38:39], s[98:99] op_sel_hi:[1,0]
	v_pk_mul_f32 v[216:217], v[34:35], s[98:99] op_sel_hi:[1,0]
	v_pk_mul_f32 v[218:219], v[32:33], s[98:99] op_sel_hi:[1,0]
	v_exp_f32_e32 v212, v212
	v_exp_f32_e32 v213, v213
	v_exp_f32_e32 v214, v214
	v_exp_f32_e32 v215, v215
	v_exp_f32_e32 v216, v216
	v_exp_f32_e32 v217, v217
	v_exp_f32_e32 v218, v218
	v_exp_f32_e32 v219, v219
	v_pk_add_f32 v[212:213], v[212:213], s[100:101] op_sel_hi:[1,0]
	v_pk_add_f32 v[214:215], v[214:215], s[100:101] op_sel_hi:[1,0]
	v_pk_add_f32 v[216:217], v[216:217], s[100:101] op_sel_hi:[1,0]
	v_pk_add_f32 v[218:219], v[218:219], s[100:101] op_sel_hi:[1,0]
	v_rcp_f32_e32 v212, v212
	v_rcp_f32_e32 v213, v213
	v_rcp_f32_e32 v214, v214
	v_rcp_f32_e32 v215, v215
	v_rcp_f32_e32 v216, v216
	v_rcp_f32_e32 v217, v217
	v_rcp_f32_e32 v218, v218
	v_rcp_f32_e32 v219, v219
	v_pk_mul_f32 v[42:43], v[36:37], v[212:213]
	v_pk_mul_f32 v[40:41], v[38:39], v[214:215]
	v_pk_mul_f32 v[44:45], v[34:35], v[216:217]
	v_pk_mul_f32 v[46:47], v[32:33], v[218:219]
	s_ashr_i32 s69, s68, 31
	v_cvt_pk_bf16_f32 v50, v42, v43
	v_cvt_pk_bf16_f32 v51, v40, v41
	v_lshl_add_u64 v[40:41], s[42:43], 0, v[48:49]
	v_lshl_add_u64 v[42:43], s[68:69], 0, v[138:139]
	v_cvt_pk_bf16_f32 v52, v46, v47
	v_cvt_pk_bf16_f32 v53, v44, v45
	v_lshl_add_u64 v[40:41], v[42:43], 1, v[40:41]
	global_store_dwordx4 v[40:41], v[50:53], off offset:-1024 nt
	s_add_i32 s21, s57, 0xa0
	v_or_b32_e32 v32, s21, v162
	v_ashrrev_i32_e32 v33, 31, v32
	v_lshlrev_b64 v[34:35], 10, v[32:33]
	v_mad_i64_i32 v[32:33], s[74:75], v32, s10, 0
	v_pk_mul_f32 v[212:213], v[28:29], s[98:99] op_sel_hi:[1,0]
	v_pk_mul_f32 v[214:215], v[30:31], s[98:99] op_sel_hi:[1,0]
	v_pk_mul_f32 v[216:217], v[26:27], s[98:99] op_sel_hi:[1,0]
	v_pk_mul_f32 v[218:219], v[24:25], s[98:99] op_sel_hi:[1,0]
	v_exp_f32_e32 v212, v212
	v_exp_f32_e32 v213, v213
	v_exp_f32_e32 v214, v214
	v_exp_f32_e32 v215, v215
	v_exp_f32_e32 v216, v216
	v_exp_f32_e32 v217, v217
	v_exp_f32_e32 v218, v218
	v_exp_f32_e32 v219, v219
	v_pk_add_f32 v[212:213], v[212:213], s[100:101] op_sel_hi:[1,0]
	v_pk_add_f32 v[214:215], v[214:215], s[100:101] op_sel_hi:[1,0]
	v_pk_add_f32 v[216:217], v[216:217], s[100:101] op_sel_hi:[1,0]
	v_pk_add_f32 v[218:219], v[218:219], s[100:101] op_sel_hi:[1,0]
	v_rcp_f32_e32 v212, v212
	v_rcp_f32_e32 v213, v213
	v_rcp_f32_e32 v214, v214
	v_rcp_f32_e32 v215, v215
	v_rcp_f32_e32 v216, v216
	v_rcp_f32_e32 v217, v217
	v_rcp_f32_e32 v218, v218
	v_rcp_f32_e32 v219, v219
	v_pk_mul_f32 v[38:39], v[28:29], v[212:213]
	v_pk_mul_f32 v[36:37], v[30:31], v[214:215]
	v_pk_mul_f32 v[40:41], v[26:27], v[216:217]
	v_pk_mul_f32 v[42:43], v[24:25], v[218:219]
	s_ashr_i32 s69, s68, 31
; #define GAS __attribute__((address_space(1)))
; __device__ __forceinline__ float siluf_(float x) { return x * sigmoidf_(x); }
; __device__ __forceinline__ u32x4 pack8(f32x4 a, f32x4 b) { u32x4 w; w.x = pk2(a[0], a[1]); w.y = pk2(a[2], a[3]); w.z = pk2(b[0], b[1]); w.w = pk2(b[2], b[3]); return w; }
;     __device__ __forceinline__ void operator()(const Unit& u, int row, int col, f32x4 v0, f32x4 v1) const {
;     ...
; #pragma unroll
;                 for (int i = 0; i < 4; ++i) { v0[i] = siluf_(v0[i]); v1[i] = siluf_(v1[i]); }
;             }
;             __builtin_nontemporal_store(pack8(v0, v1), (GAS u32x4*)(P + (size_t)row * PW + pc));
	v_cvt_pk_bf16_f32 v44, v38, v39
	v_cvt_pk_bf16_f32 v45, v36, v37
	v_lshl_add_u64 v[36:37], s[42:43], 0, v[32:33]
	v_lshl_add_u64 v[38:39], s[68:69], 0, v[136:137]
	v_cvt_pk_bf16_f32 v46, v42, v43
	v_cvt_pk_bf16_f32 v47, v40, v41
	v_lshl_add_u64 v[36:37], v[38:39], 1, v[36:37]
	global_store_dwordx4 v[36:37], v[44:47], off offset:-1024 nt
	s_ashr_i32 s21, s21, 4
	v_pk_mul_f32 v[212:213], v[20:21], s[98:99] op_sel_hi:[1,0]
	v_pk_mul_f32 v[214:215], v[22:23], s[98:99] op_sel_hi:[1,0]
	v_pk_mul_f32 v[216:217], v[18:19], s[98:99] op_sel_hi:[1,0]
	v_pk_mul_f32 v[218:219], v[16:17], s[98:99] op_sel_hi:[1,0]
	v_exp_f32_e32 v212, v212
	v_exp_f32_e32 v213, v213
	v_exp_f32_e32 v214, v214
	v_exp_f32_e32 v215, v215
	v_exp_f32_e32 v216, v216
	v_exp_f32_e32 v217, v217
	v_exp_f32_e32 v218, v218
	v_exp_f32_e32 v219, v219
	v_pk_add_f32 v[212:213], v[212:213], s[100:101] op_sel_hi:[1,0]
	v_pk_add_f32 v[214:215], v[214:215], s[100:101] op_sel_hi:[1,0]
	v_pk_add_f32 v[216:217], v[216:217], s[100:101] op_sel_hi:[1,0]
	v_pk_add_f32 v[218:219], v[218:219], s[100:101] op_sel_hi:[1,0]
	v_rcp_f32_e32 v212, v212
	v_rcp_f32_e32 v213, v213
	v_rcp_f32_e32 v214, v214
	v_rcp_f32_e32 v215, v215
	v_rcp_f32_e32 v216, v216
	v_rcp_f32_e32 v217, v217
	v_rcp_f32_e32 v218, v218
	v_rcp_f32_e32 v219, v219
	v_pk_mul_f32 v[26:27], v[20:21], v[212:213]
	v_pk_mul_f32 v[24:25], v[22:23], v[214:215]
	v_pk_mul_f32 v[28:29], v[18:19], v[216:217]
	v_pk_mul_f32 v[30:31], v[16:17], v[218:219]
	s_ashr_i32 s69, s68, 31
	v_cvt_pk_bf16_f32 v34, v26, v27
	v_cvt_pk_bf16_f32 v35, v24, v25
	v_lshl_add_u64 v[24:25], s[42:43], 0, v[32:33]
	v_lshl_add_u64 v[26:27], s[68:69], 0, v[138:139]
	v_cvt_pk_bf16_f32 v36, v30, v31
	v_cvt_pk_bf16_f32 v37, v28, v29
	v_lshl_add_u64 v[24:25], v[26:27], 1, v[24:25]
	global_store_dwordx4 v[24:25], v[34:37], off offset:-1024 nt
	s_addk_i32 s57, 0xb0
	v_or_b32_e32 v16, s57, v162
	v_ashrrev_i32_e32 v17, 31, v16
	v_lshlrev_b64 v[18:19], 10, v[16:17]
	v_mad_i64_i32 v[16:17], s[74:75], v16, s10, 0
	v_pk_mul_f32 v[212:213], v[12:13], s[98:99] op_sel_hi:[1,0]
	v_pk_mul_f32 v[214:215], v[14:15], s[98:99] op_sel_hi:[1,0]
	v_pk_mul_f32 v[216:217], v[10:11], s[98:99] op_sel_hi:[1,0]
	v_pk_mul_f32 v[218:219], v[8:9], s[98:99] op_sel_hi:[1,0]
	v_exp_f32_e32 v212, v212
	v_exp_f32_e32 v213, v213
	v_exp_f32_e32 v214, v214
	v_exp_f32_e32 v215, v215
	v_exp_f32_e32 v216, v216
	v_exp_f32_e32 v217, v217
	v_exp_f32_e32 v218, v218
	v_exp_f32_e32 v219, v219
	v_pk_add_f32 v[212:213], v[212:213], s[100:101] op_sel_hi:[1,0]
	v_pk_add_f32 v[214:215], v[214:215], s[100:101] op_sel_hi:[1,0]
	v_pk_add_f32 v[216:217], v[216:217], s[100:101] op_sel_hi:[1,0]
	v_pk_add_f32 v[218:219], v[218:219], s[100:101] op_sel_hi:[1,0]
	v_rcp_f32_e32 v212, v212
	v_rcp_f32_e32 v213, v213
	v_rcp_f32_e32 v214, v214
	v_rcp_f32_e32 v215, v215
	v_rcp_f32_e32 v216, v216
	v_rcp_f32_e32 v217, v217
	v_rcp_f32_e32 v218, v218
	v_rcp_f32_e32 v219, v219
	v_pk_mul_f32 v[22:23], v[12:13], v[212:213]
	v_pk_mul_f32 v[20:21], v[14:15], v[214:215]
	v_pk_mul_f32 v[24:25], v[10:11], v[216:217]
	v_pk_mul_f32 v[26:27], v[8:9], v[218:219]
	s_ashr_i32 s69, s68, 31
	v_cvt_pk_bf16_f32 v28, v22, v23
	v_cvt_pk_bf16_f32 v29, v20, v21
	v_lshl_add_u64 v[20:21], s[42:43], 0, v[16:17]
	v_lshl_add_u64 v[22:23], s[68:69], 0, v[136:137]
	v_cvt_pk_bf16_f32 v30, v26, v27
	v_cvt_pk_bf16_f32 v31, v24, v25
	v_lshl_add_u64 v[20:21], v[22:23], 1, v[20:21]
	global_store_dwordx4 v[20:21], v[28:31], off offset:-1024 nt
	s_ashr_i32 s21, s57, 4
	v_pk_mul_f32 v[212:213], v[4:5], s[98:99] op_sel_hi:[1,0]
	v_pk_mul_f32 v[214:215], v[6:7], s[98:99] op_sel_hi:[1,0]
	v_pk_mul_f32 v[216:217], v[2:3], s[98:99] op_sel_hi:[1,0]
	v_pk_mul_f32 v[218:219], v[0:1], s[98:99] op_sel_hi:[1,0]
	v_exp_f32_e32 v212, v212
	v_exp_f32_e32 v213, v213
	v_exp_f32_e32 v214, v214
	v_exp_f32_e32 v215, v215
	v_exp_f32_e32 v216, v216
	v_exp_f32_e32 v217, v217
	v_exp_f32_e32 v218, v218
	v_exp_f32_e32 v219, v219
	v_pk_add_f32 v[212:213], v[212:213], s[100:101] op_sel_hi:[1,0]
	v_pk_add_f32 v[214:215], v[214:215], s[100:101] op_sel_hi:[1,0]
	v_pk_add_f32 v[216:217], v[216:217], s[100:101] op_sel_hi:[1,0]
	v_pk_add_f32 v[218:219], v[218:219], s[100:101] op_sel_hi:[1,0]
	v_rcp_f32_e32 v212, v212
	v_rcp_f32_e32 v213, v213
	v_rcp_f32_e32 v214, v214
	v_rcp_f32_e32 v215, v215
	v_rcp_f32_e32 v216, v216
	v_rcp_f32_e32 v217, v217
	v_rcp_f32_e32 v218, v218
	v_rcp_f32_e32 v219, v219
	v_pk_mul_f32 v[10:11], v[4:5], v[212:213]
	v_pk_mul_f32 v[8:9], v[6:7], v[214:215]
	v_pk_mul_f32 v[12:13], v[2:3], v[216:217]
	v_pk_mul_f32 v[14:15], v[0:1], v[218:219]
	s_ashr_i32 s69, s68, 31
	v_cvt_pk_bf16_f32 v18, v10, v11
	v_cvt_pk_bf16_f32 v19, v8, v9
	v_lshl_add_u64 v[8:9], s[42:43], 0, v[16:17]
	v_lshl_add_u64 v[10:11], s[68:69], 0, v[138:139]
	v_cvt_pk_bf16_f32 v20, v14, v15
	v_cvt_pk_bf16_f32 v21, v12, v13
	v_lshl_add_u64 v[8:9], v[10:11], 1, v[8:9]
	global_store_dwordx4 v[8:9], v[18:21], off offset:-1024 nt
	s_andn2_b64 vcc, exec, s[4:5]
	s_mov_b64 s[4:5], -1
	s_cbranch_vccnz .LBB0_178
	s_andn2_b64 vcc, exec, s[40:41]
	s_cbranch_vccnz .LBB0_177
	s_barrier
	s_branch .LBB0_177
; #define GAS __attribute__((address_space(1)))
; __device__ __forceinline__ float siluf_(float x) { return x * sigmoidf_(x); }
; __device__ __forceinline__ u32x4 pack8(f32x4 a, f32x4 b) { u32x4 w; w.x = pk2(a[0], a[1]); w.y = pk2(a[2], a[3]); w.z = pk2(b[0], b[1]); w.w = pk2(b[2], b[3]); return w; }
;     __device__ __forceinline__ void operator()(const Unit& u, int row, int col, f32x4 v0, f32x4 v1) const {
;     ...
;             } else if (pn == 8 || pn == 9) {
;                 const float sc = 0.08838834764831845f * LOG2E;
;                 v0 = v0 * sc; v1 = v1 * sc;
;             } else {
; #pragma unroll
;                 for (int i = 0; i < 4; ++i) { v0[i] = siluf_(v0[i]); v1[i] = siluf_(v1[i]); }
;             }
;             __builtin_nontemporal_store(pack8(v0, v1), (GAS u32x4*)(P + (size_t)row * PW + pc));
.Lfp_cls2:
	s_mov_b32 s98, 0xbfb8aa3b
	s_mov_b32 s100, 1.0
	s_lshl_b32 s57, s6, 8
	s_add_i32 s57, s57, s85
	s_lshl_b32 s68, s76, 8
	s_add_i32 s38, s68, 0xffffea00
	v_or_b32_e32 v150, s57, v162
	s_and_b32 s8, s76, 14
	v_ashrrev_i32_e32 v151, 31, v150
	v_lshlrev_b64 v[152:153], 10, v[150:151]
	v_mad_i64_i32 v[150:151], s[8:9], v150, s10, 0
	v_pk_mul_f32 v[154:155], v[122:123], s[52:53] op_sel_hi:[1,0]
	v_pk_mul_f32 v[156:157], v[120:121], s[52:53] op_sel_hi:[1,0]
	v_pk_mul_f32 v[158:159], v[126:127], s[52:53] op_sel_hi:[1,0]
	v_pk_mul_f32 v[160:161], v[124:125], s[52:53] op_sel_hi:[1,0]
	s_ashr_i32 s69, s68, 31
	v_cvt_pk_bf16_f32 v170, v156, v157
	v_cvt_pk_bf16_f32 v171, v154, v155
	v_lshl_add_u64 v[154:155], s[42:43], 0, v[150:151]
	v_lshl_add_u64 v[156:157], s[68:69], 0, v[136:137]
	v_cvt_pk_bf16_f32 v172, v160, v161
	v_cvt_pk_bf16_f32 v173, v158, v159
	v_lshl_add_u64 v[154:155], v[156:157], 1, v[154:155]
	global_store_dwordx4 v[154:155], v[170:173], off offset:-1024 nt
	s_lshl_b32 s21, s76, 15
	v_add_u32_e32 v154, s21, v164
	s_ashr_i32 s59, s57, 4
	v_and_b32_e32 v154, 0xfffff800, v154
	s_nop 1
	v_pk_mul_f32 v[120:121], v[118:119], s[52:53] op_sel_hi:[1,0]
	v_pk_mul_f32 v[122:123], v[116:117], s[52:53] op_sel_hi:[1,0]
	v_pk_mul_f32 v[124:125], v[114:115], s[52:53] op_sel_hi:[1,0]
	v_pk_mul_f32 v[126:127], v[112:113], s[52:53] op_sel_hi:[1,0]
	s_ashr_i32 s69, s68, 31
	v_cvt_pk_bf16_f32 v156, v122, v123
	v_cvt_pk_bf16_f32 v157, v120, v121
	v_lshl_add_u64 v[120:121], s[42:43], 0, v[150:151]
	v_lshl_add_u64 v[122:123], s[68:69], 0, v[138:139]
	v_cvt_pk_bf16_f32 v158, v126, v127
	v_cvt_pk_bf16_f32 v159, v124, v125
	v_lshl_add_u64 v[120:121], v[122:123], 1, v[120:121]
	global_store_dwordx4 v[120:121], v[156:159], off offset:-1024 nt
	v_add_u32_e32 v120, s21, v165
	v_and_b32_e32 v124, 0xfffff800, v120
	s_or_b32 s21, s57, 16
	v_or_b32_e32 v112, s21, v162
	v_ashrrev_i32_e32 v113, 31, v112
	v_lshlrev_b64 v[114:115], 10, v[112:113]
	v_mad_i64_i32 v[112:113], s[74:75], v112, s10, 0
	v_pk_mul_f32 v[116:117], v[110:111], s[52:53] op_sel_hi:[1,0]
	v_pk_mul_f32 v[118:119], v[108:109], s[52:53] op_sel_hi:[1,0]
	v_pk_mul_f32 v[120:121], v[106:107], s[52:53] op_sel_hi:[1,0]
	v_pk_mul_f32 v[122:123], v[104:105], s[52:53] op_sel_hi:[1,0]
	s_ashr_i32 s69, s68, 31
	v_cvt_pk_bf16_f32 v150, v118, v119
	v_cvt_pk_bf16_f32 v151, v116, v117
	v_lshl_add_u64 v[116:117], s[42:43], 0, v[112:113]
	v_lshl_add_u64 v[118:119], s[68:69], 0, v[136:137]
	v_cvt_pk_bf16_f32 v152, v122, v123
	v_cvt_pk_bf16_f32 v153, v120, v121
	v_lshl_add_u64 v[116:117], v[118:119], 1, v[116:117]
	global_store_dwordx4 v[116:117], v[150:153], off offset:-1024 nt
	s_ashr_i32 s21, s21, 4
	v_pk_mul_f32 v[104:105], v[102:103], s[52:53] op_sel_hi:[1,0]
	v_pk_mul_f32 v[106:107], v[100:101], s[52:53] op_sel_hi:[1,0]
	v_pk_mul_f32 v[108:109], v[98:99], s[52:53] op_sel_hi:[1,0]
	v_pk_mul_f32 v[110:111], v[96:97], s[52:53] op_sel_hi:[1,0]
	s_ashr_i32 s69, s68, 31
	v_cvt_pk_bf16_f32 v114, v106, v107
	v_cvt_pk_bf16_f32 v115, v104, v105
	v_lshl_add_u64 v[104:105], s[42:43], 0, v[112:113]
	v_lshl_add_u64 v[106:107], s[68:69], 0, v[138:139]
	v_cvt_pk_bf16_f32 v116, v110, v111
	v_cvt_pk_bf16_f32 v117, v108, v109
	v_lshl_add_u64 v[104:105], v[106:107], 1, v[104:105]
	global_store_dwordx4 v[104:105], v[114:117], off offset:-1024 nt
	s_or_b32 s21, s57, 32
	v_or_b32_e32 v96, s21, v162
	v_ashrrev_i32_e32 v97, 31, v96
	v_lshlrev_b64 v[98:99], 10, v[96:97]
	v_mad_i64_i32 v[96:97], s[74:75], v96, s10, 0
	v_pk_mul_f32 v[100:101], v[94:95], s[52:53] op_sel_hi:[1,0]
	v_pk_mul_f32 v[102:103], v[92:93], s[52:53] op_sel_hi:[1,0]
	v_pk_mul_f32 v[104:105], v[90:91], s[52:53] op_sel_hi:[1,0]
	v_pk_mul_f32 v[106:107], v[88:89], s[52:53] op_sel_hi:[1,0]
	s_ashr_i32 s69, s68, 31
	v_cvt_pk_bf16_f32 v108, v102, v103
	v_cvt_pk_bf16_f32 v109, v100, v101
	v_lshl_add_u64 v[100:101], s[42:43], 0, v[96:97]
	v_lshl_add_u64 v[102:103], s[68:69], 0, v[136:137]
	v_cvt_pk_bf16_f32 v110, v106, v107
	v_cvt_pk_bf16_f32 v111, v104, v105
	v_lshl_add_u64 v[100:101], v[102:103], 1, v[100:101]
	global_store_dwordx4 v[100:101], v[108:111], off offset:-1024 nt
	s_ashr_i32 s21, s21, 4
	v_pk_mul_f32 v[88:89], v[86:87], s[52:53] op_sel_hi:[1,0]
	v_pk_mul_f32 v[90:91], v[84:85], s[52:53] op_sel_hi:[1,0]
	v_pk_mul_f32 v[92:93], v[82:83], s[52:53] op_sel_hi:[1,0]
	v_pk_mul_f32 v[94:95], v[80:81], s[52:53] op_sel_hi:[1,0]
	s_ashr_i32 s69, s68, 31
	v_cvt_pk_bf16_f32 v98, v90, v91
	v_cvt_pk_bf16_f32 v99, v88, v89
	v_lshl_add_u64 v[88:89], s[42:43], 0, v[96:97]
	v_lshl_add_u64 v[90:91], s[68:69], 0, v[138:139]
	v_cvt_pk_bf16_f32 v100, v94, v95
	v_cvt_pk_bf16_f32 v101, v92, v93
	v_lshl_add_u64 v[88:89], v[90:91], 1, v[88:89]
	global_store_dwordx4 v[88:89], v[98:101], off offset:-1024 nt
	s_or_b32 s21, s57, 48
	v_or_b32_e32 v80, s21, v162
	v_ashrrev_i32_e32 v81, 31, v80
	v_lshlrev_b64 v[82:83], 10, v[80:81]
	v_mad_i64_i32 v[80:81], s[74:75], v80, s10, 0
	v_pk_mul_f32 v[84:85], v[78:79], s[52:53] op_sel_hi:[1,0]
	v_pk_mul_f32 v[86:87], v[76:77], s[52:53] op_sel_hi:[1,0]
	v_pk_mul_f32 v[88:89], v[74:75], s[52:53] op_sel_hi:[1,0]
	v_pk_mul_f32 v[90:91], v[72:73], s[52:53] op_sel_hi:[1,0]
	s_ashr_i32 s69, s68, 31
	v_cvt_pk_bf16_f32 v92, v86, v87
	v_cvt_pk_bf16_f32 v93, v84, v85
	v_lshl_add_u64 v[84:85], s[42:43], 0, v[80:81]
	v_lshl_add_u64 v[86:87], s[68:69], 0, v[136:137]
	v_cvt_pk_bf16_f32 v94, v90, v91
	v_cvt_pk_bf16_f32 v95, v88, v89
	v_lshl_add_u64 v[84:85], v[86:87], 1, v[84:85]
	global_store_dwordx4 v[84:85], v[92:95], off offset:-1024 nt
	s_ashr_i32 s21, s21, 4
	v_pk_mul_f32 v[72:73], v[70:71], s[52:53] op_sel_hi:[1,0]
	v_pk_mul_f32 v[74:75], v[68:69], s[52:53] op_sel_hi:[1,0]
; #define GAS __attribute__((address_space(1)))
; __device__ __forceinline__ float siluf_(float x) { return x * sigmoidf_(x); }
; __device__ __forceinline__ u32x4 pack8(f32x4 a, f32x4 b) { u32x4 w; w.x = pk2(a[0], a[1]); w.y = pk2(a[2], a[3]); w.z = pk2(b[0], b[1]); w.w = pk2(b[2], b[3]); return w; }
;     __device__ __forceinline__ void operator()(const Unit& u, int row, int col, f32x4 v0, f32x4 v1) const {
;     ...
;             } else if (pn == 8 || pn == 9) {
;                 const float sc = 0.08838834764831845f * LOG2E;
;                 v0 = v0 * sc; v1 = v1 * sc;
;             } else {
; #pragma unroll
;                 for (int i = 0; i < 4; ++i) { v0[i] = siluf_(v0[i]); v1[i] = siluf_(v1[i]); }
;             }
;             __builtin_nontemporal_store(pack8(v0, v1), (GAS u32x4*)(P + (size_t)row * PW + pc));
	v_pk_mul_f32 v[76:77], v[66:67], s[52:53] op_sel_hi:[1,0]
	v_pk_mul_f32 v[78:79], v[64:65], s[52:53] op_sel_hi:[1,0]
	s_ashr_i32 s69, s68, 31
	v_cvt_pk_bf16_f32 v82, v74, v75
	v_cvt_pk_bf16_f32 v83, v72, v73
	v_lshl_add_u64 v[72:73], s[42:43], 0, v[80:81]
	v_lshl_add_u64 v[74:75], s[68:69], 0, v[138:139]
	v_cvt_pk_bf16_f32 v84, v78, v79
	v_cvt_pk_bf16_f32 v85, v76, v77
	v_lshl_add_u64 v[72:73], v[74:75], 1, v[72:73]
	global_store_dwordx4 v[72:73], v[82:85], off offset:-1024 nt
	s_add_i32 s21, s57, 0x80
	v_or_b32_e32 v64, s21, v162
	v_ashrrev_i32_e32 v65, 31, v64
	v_lshlrev_b64 v[66:67], 10, v[64:65]
	v_mad_i64_i32 v[64:65], s[74:75], v64, s10, 0
	v_pk_mul_f32 v[68:69], v[62:63], s[52:53] op_sel_hi:[1,0]
	v_pk_mul_f32 v[70:71], v[60:61], s[52:53] op_sel_hi:[1,0]
	v_pk_mul_f32 v[72:73], v[58:59], s[52:53] op_sel_hi:[1,0]
	v_pk_mul_f32 v[74:75], v[56:57], s[52:53] op_sel_hi:[1,0]
	s_ashr_i32 s69, s68, 31
	v_cvt_pk_bf16_f32 v76, v70, v71
	v_cvt_pk_bf16_f32 v77, v68, v69
	v_lshl_add_u64 v[68:69], s[42:43], 0, v[64:65]
	v_lshl_add_u64 v[70:71], s[68:69], 0, v[136:137]
	v_cvt_pk_bf16_f32 v78, v74, v75
	v_cvt_pk_bf16_f32 v79, v72, v73
	v_lshl_add_u64 v[68:69], v[70:71], 1, v[68:69]
	global_store_dwordx4 v[68:69], v[76:79], off offset:-1024 nt
	s_ashr_i32 s21, s21, 4
	v_pk_mul_f32 v[56:57], v[54:55], s[52:53] op_sel_hi:[1,0]
	v_pk_mul_f32 v[58:59], v[52:53], s[52:53] op_sel_hi:[1,0]
	v_pk_mul_f32 v[60:61], v[50:51], s[52:53] op_sel_hi:[1,0]
	v_pk_mul_f32 v[62:63], v[48:49], s[52:53] op_sel_hi:[1,0]
	s_ashr_i32 s69, s68, 31
	v_cvt_pk_bf16_f32 v66, v58, v59
	v_cvt_pk_bf16_f32 v67, v56, v57
	v_lshl_add_u64 v[56:57], s[42:43], 0, v[64:65]
	v_lshl_add_u64 v[58:59], s[68:69], 0, v[138:139]
	v_cvt_pk_bf16_f32 v68, v62, v63
	v_cvt_pk_bf16_f32 v69, v60, v61
	v_lshl_add_u64 v[56:57], v[58:59], 1, v[56:57]
	global_store_dwordx4 v[56:57], v[66:69], off offset:-1024 nt
	s_add_i32 s21, s57, 0x90
	v_or_b32_e32 v48, s21, v162
	v_ashrrev_i32_e32 v49, 31, v48
	v_lshlrev_b64 v[50:51], 10, v[48:49]
	v_mad_i64_i32 v[48:49], s[74:75], v48, s10, 0
	v_pk_mul_f32 v[52:53], v[46:47], s[52:53] op_sel_hi:[1,0]
	v_pk_mul_f32 v[54:55], v[44:45], s[52:53] op_sel_hi:[1,0]
	v_pk_mul_f32 v[56:57], v[42:43], s[52:53] op_sel_hi:[1,0]
	v_pk_mul_f32 v[58:59], v[40:41], s[52:53] op_sel_hi:[1,0]
	s_ashr_i32 s69, s68, 31
	v_cvt_pk_bf16_f32 v60, v54, v55
	v_cvt_pk_bf16_f32 v61, v52, v53
	v_lshl_add_u64 v[52:53], s[42:43], 0, v[48:49]
	v_lshl_add_u64 v[54:55], s[68:69], 0, v[136:137]
	v_cvt_pk_bf16_f32 v62, v58, v59
	v_cvt_pk_bf16_f32 v63, v56, v57
	v_lshl_add_u64 v[52:53], v[54:55], 1, v[52:53]
	global_store_dwordx4 v[52:53], v[60:63], off offset:-1024 nt
	s_ashr_i32 s21, s21, 4
	v_pk_mul_f32 v[40:41], v[38:39], s[52:53] op_sel_hi:[1,0]
	v_pk_mul_f32 v[42:43], v[36:37], s[52:53] op_sel_hi:[1,0]
	v_pk_mul_f32 v[44:45], v[34:35], s[52:53] op_sel_hi:[1,0]
	v_pk_mul_f32 v[46:47], v[32:33], s[52:53] op_sel_hi:[1,0]
	s_ashr_i32 s69, s68, 31
	v_cvt_pk_bf16_f32 v50, v42, v43
	v_cvt_pk_bf16_f32 v51, v40, v41
	v_lshl_add_u64 v[40:41], s[42:43], 0, v[48:49]
	v_lshl_add_u64 v[42:43], s[68:69], 0, v[138:139]
	v_cvt_pk_bf16_f32 v52, v46, v47
	v_cvt_pk_bf16_f32 v53, v44, v45
	v_lshl_add_u64 v[40:41], v[42:43], 1, v[40:41]
	global_store_dwordx4 v[40:41], v[50:53], off offset:-1024 nt
	s_add_i32 s21, s57, 0xa0
	v_or_b32_e32 v32, s21, v162
	v_ashrrev_i32_e32 v33, 31, v32
	v_lshlrev_b64 v[34:35], 10, v[32:33]
	v_mad_i64_i32 v[32:33], s[74:75], v32, s10, 0
	v_pk_mul_f32 v[36:37], v[30:31], s[52:53] op_sel_hi:[1,0]
	v_pk_mul_f32 v[38:39], v[28:29], s[52:53] op_sel_hi:[1,0]
	v_pk_mul_f32 v[40:41], v[26:27], s[52:53] op_sel_hi:[1,0]
	v_pk_mul_f32 v[42:43], v[24:25], s[52:53] op_sel_hi:[1,0]
	s_ashr_i32 s69, s68, 31
	v_cvt_pk_bf16_f32 v44, v38, v39
	v_cvt_pk_bf16_f32 v45, v36, v37
	v_lshl_add_u64 v[36:37], s[42:43], 0, v[32:33]
	v_lshl_add_u64 v[38:39], s[68:69], 0, v[136:137]
	v_cvt_pk_bf16_f32 v46, v42, v43
	v_cvt_pk_bf16_f32 v47, v40, v41
	v_lshl_add_u64 v[36:37], v[38:39], 1, v[36:37]
	global_store_dwordx4 v[36:37], v[44:47], off offset:-1024 nt
	s_ashr_i32 s21, s21, 4
	v_pk_mul_f32 v[24:25], v[22:23], s[52:53] op_sel_hi:[1,0]
	v_pk_mul_f32 v[26:27], v[20:21], s[52:53] op_sel_hi:[1,0]
	v_pk_mul_f32 v[28:29], v[18:19], s[52:53] op_sel_hi:[1,0]
	v_pk_mul_f32 v[30:31], v[16:17], s[52:53] op_sel_hi:[1,0]
	s_ashr_i32 s69, s68, 31
	v_cvt_pk_bf16_f32 v34, v26, v27
	v_cvt_pk_bf16_f32 v35, v24, v25
	v_lshl_add_u64 v[24:25], s[42:43], 0, v[32:33]
	v_lshl_add_u64 v[26:27], s[68:69], 0, v[138:139]
	v_cvt_pk_bf16_f32 v36, v30, v31
	v_cvt_pk_bf16_f32 v37, v28, v29
	v_lshl_add_u64 v[24:25], v[26:27], 1, v[24:25]
	global_store_dwordx4 v[24:25], v[34:37], off offset:-1024 nt
	s_addk_i32 s57, 0xb0
	v_or_b32_e32 v16, s57, v162
	v_ashrrev_i32_e32 v17, 31, v16
	v_lshlrev_b64 v[18:19], 10, v[16:17]
	v_mad_i64_i32 v[16:17], s[74:75], v16, s10, 0
	v_pk_mul_f32 v[20:21], v[14:15], s[52:53] op_sel_hi:[1,0]
	v_pk_mul_f32 v[22:23], v[12:13], s[52:53] op_sel_hi:[1,0]
	v_pk_mul_f32 v[24:25], v[10:11], s[52:53] op_sel_hi:[1,0]
	v_pk_mul_f32 v[26:27], v[8:9], s[52:53] op_sel_hi:[1,0]
	s_ashr_i32 s69, s68, 31
	v_cvt_pk_bf16_f32 v28, v22, v23
	v_cvt_pk_bf16_f32 v29, v20, v21
	v_lshl_add_u64 v[20:21], s[42:43], 0, v[16:17]
	v_lshl_add_u64 v[22:23], s[68:69], 0, v[136:137]
	v_cvt_pk_bf16_f32 v30, v26, v27
	v_cvt_pk_bf16_f32 v31, v24, v25
	v_lshl_add_u64 v[20:21], v[22:23], 1, v[20:21]
	global_store_dwordx4 v[20:21], v[28:31], off offset:-1024 nt
	s_ashr_i32 s21, s57, 4
	v_pk_mul_f32 v[8:9], v[6:7], s[52:53] op_sel_hi:[1,0]
	v_pk_mul_f32 v[10:11], v[4:5], s[52:53] op_sel_hi:[1,0]
	v_pk_mul_f32 v[12:13], v[2:3], s[52:53] op_sel_hi:[1,0]
	v_pk_mul_f32 v[14:15], v[0:1], s[52:53] op_sel_hi:[1,0]
	s_ashr_i32 s69, s68, 31
	v_cvt_pk_bf16_f32 v18, v10, v11
	v_cvt_pk_bf16_f32 v19, v8, v9
	v_lshl_add_u64 v[8:9], s[42:43], 0, v[16:17]
	v_lshl_add_u64 v[10:11], s[68:69], 0, v[138:139]
	v_cvt_pk_bf16_f32 v20, v14, v15
	v_cvt_pk_bf16_f32 v21, v12, v13
	v_lshl_add_u64 v[8:9], v[10:11], 1, v[8:9]
	global_store_dwordx4 v[8:9], v[18:21], off offset:-1024 nt
	s_andn2_b64 vcc, exec, s[4:5]
	s_mov_b64 s[4:5], -1
	s_cbranch_vccnz .LBB0_178
	s_andn2_b64 vcc, exec, s[40:41]
	s_cbranch_vccnz .LBB0_177
	s_barrier
	s_branch .LBB0_177
; #define GAS __attribute__((address_space(1)))
; __device__ __forceinline__ float sigmoidf_(float x) { return frcp(1.f + fexp2(-x * LOG2E)); }
; __device__ __forceinline__ float siluf_(float x) { return x * sigmoidf_(x); }
; __device__ __forceinline__ u32x4 pack8(f32x4 a, f32x4 b) { u32x4 w; w.x = pk2(a[0], a[1]); w.y = pk2(a[2], a[3]); w.z = pk2(b[0], b[1]); w.w = pk2(b[2], b[3]); return w; }
;     __device__ __forceinline__ void operator()(const Unit& u, int row, int col, f32x4 v0, f32x4 v1) const {
;     ...
;             const int pc = pn * 256 - 512 + col;
;             if (pn >= 10) {
;                 const f32x4 b0 = *(const GAS f32x4*)(b_gate + pc - PC_GATE), b1 = *(const GAS f32x4*)(b_gate + pc - PC_GATE + 4);
; #pragma unroll
;                 for (int i = 0; i < 4; ++i) { v0[i] = sigmoidf_(v0[i] + b0[i]); v1[i] = sigmoidf_(v1[i] + b1[i]); }
;             } else if (pn == 8 || pn == 9) {
;                 const float sc = 0.08838834764831845f * LOG2E;
;                 v0 = v0 * sc; v1 = v1 * sc;
;             } else {
; #pragma unroll
;                 for (int i = 0; i < 4; ++i) { v0[i] = siluf_(v0[i]); v1[i] = siluf_(v1[i]); }
;             }
;             __builtin_nontemporal_store(pack8(v0, v1), (GAS u32x4*)(P + (size_t)row * PW + pc));
.Lfp_cls3:
	s_mov_b32 s98, 0xbfb8aa3b
	s_mov_b32 s100, 1.0
	s_lshl_b32 s57, s6, 8
	s_add_i32 s57, s57, s85
	s_lshl_b32 s68, s76, 8
	s_add_i32 s38, s68, 0xffffea00
	v_or_b32_e32 v150, s57, v162
	s_and_b32 s8, s76, 14
	v_ashrrev_i32_e32 v151, 31, v150
	v_lshlrev_b64 v[152:153], 10, v[150:151]
	v_mad_i64_i32 v[150:151], s[8:9], v150, s10, 0
	s_ashr_i32 s69, s68, 31
	v_lshl_add_u64 v[196:197], s[68:69], 0, v[136:137]
	v_lshl_add_u64 v[204:205], s[68:69], 0, v[138:139]
	s_waitcnt lgkmcnt(0)
	v_lshl_add_u64 v[196:197], v[196:197], 2, s[36:37]
	v_lshl_add_u64 v[204:205], v[204:205], 2, s[36:37]
	v_lshl_add_u64 v[200:201], v[196:197], 0, s[54:55]
	v_lshl_add_u64 v[208:209], v[204:205], 0, s[54:55]
	v_add_co_u32_e32 v196, vcc, 0xffffe000, v196
	s_nop 1
	v_addc_co_u32_e32 v197, vcc, -1, v197, vcc
	v_add_co_u32_e32 v204, vcc, 0xffffe000, v204
	s_nop 1
	v_addc_co_u32_e32 v205, vcc, -1, v205, vcc
	global_load_dwordx4 v[196:199], v[196:197], off offset:-2048
	global_load_dwordx4 v[200:203], v[200:201], off offset:16
	global_load_dwordx4 v[204:207], v[204:205], off offset:-2048
	global_load_dwordx4 v[208:211], v[208:209], off offset:16
	s_waitcnt vmcnt(2)
	v_pk_add_f32 v[212:213], v[120:121], v[196:197]
	v_pk_add_f32 v[214:215], v[122:123], v[198:199]
	v_pk_add_f32 v[216:217], v[124:125], v[200:201]
	v_pk_add_f32 v[218:219], v[126:127], v[202:203]
	v_pk_mul_f32 v[212:213], v[212:213], s[98:99] op_sel_hi:[1,0]
	v_pk_mul_f32 v[214:215], v[214:215], s[98:99] op_sel_hi:[1,0]
	v_pk_mul_f32 v[216:217], v[216:217], s[98:99] op_sel_hi:[1,0]
	v_pk_mul_f32 v[218:219], v[218:219], s[98:99] op_sel_hi:[1,0]
	v_exp_f32_e32 v212, v212
	v_exp_f32_e32 v213, v213
	v_exp_f32_e32 v214, v214
	v_exp_f32_e32 v215, v215
	v_exp_f32_e32 v216, v216
	v_exp_f32_e32 v217, v217
	v_exp_f32_e32 v218, v218
	v_exp_f32_e32 v219, v219
	v_pk_add_f32 v[212:213], v[212:213], s[100:101] op_sel_hi:[1,0]
	v_pk_add_f32 v[214:215], v[214:215], s[100:101] op_sel_hi:[1,0]
	v_pk_add_f32 v[216:217], v[216:217], s[100:101] op_sel_hi:[1,0]
	v_pk_add_f32 v[218:219], v[218:219], s[100:101] op_sel_hi:[1,0]
	v_rcp_f32_e32 v156, v212
	v_rcp_f32_e32 v157, v213
	v_rcp_f32_e32 v154, v214
	v_rcp_f32_e32 v155, v215
	v_rcp_f32_e32 v160, v216
	v_rcp_f32_e32 v161, v217
	v_rcp_f32_e32 v158, v218
	v_rcp_f32_e32 v159, v219
	s_ashr_i32 s69, s68, 31
	v_cvt_pk_bf16_f32 v170, v156, v157
	v_cvt_pk_bf16_f32 v171, v154, v155
	v_lshl_add_u64 v[154:155], s[42:43], 0, v[150:151]
	v_lshl_add_u64 v[156:157], s[68:69], 0, v[136:137]
	v_cvt_pk_bf16_f32 v172, v160, v161
	v_cvt_pk_bf16_f32 v173, v158, v159
	v_lshl_add_u64 v[154:155], v[156:157], 1, v[154:155]
	global_store_dwordx4 v[154:155], v[170:173], off offset:-1024 nt
	s_lshl_b32 s21, s76, 15
	v_add_u32_e32 v154, s21, v164
	s_ashr_i32 s59, s57, 4
	v_and_b32_e32 v154, 0xfffff800, v154
	s_nop 1
	s_waitcnt vmcnt(1)
	v_pk_add_f32 v[212:213], v[112:113], v[208:209]
	v_pk_add_f32 v[214:215], v[114:115], v[210:211]
	v_pk_add_f32 v[216:217], v[116:117], v[204:205]
	v_pk_add_f32 v[218:219], v[118:119], v[206:207]
	v_pk_mul_f32 v[212:213], v[212:213], s[98:99] op_sel_hi:[1,0]
	v_pk_mul_f32 v[214:215], v[214:215], s[98:99] op_sel_hi:[1,0]
	v_pk_mul_f32 v[216:217], v[216:217], s[98:99] op_sel_hi:[1,0]
	v_pk_mul_f32 v[218:219], v[218:219], s[98:99] op_sel_hi:[1,0]
	v_exp_f32_e32 v212, v212
	v_exp_f32_e32 v213, v213
	v_exp_f32_e32 v214, v214
	v_exp_f32_e32 v215, v215
	v_exp_f32_e32 v216, v216
	v_exp_f32_e32 v217, v217
	v_exp_f32_e32 v218, v218
	v_exp_f32_e32 v219, v219
	v_pk_add_f32 v[212:213], v[212:213], s[100:101] op_sel_hi:[1,0]
	v_pk_add_f32 v[214:215], v[214:215], s[100:101] op_sel_hi:[1,0]
	v_pk_add_f32 v[216:217], v[216:217], s[100:101] op_sel_hi:[1,0]
	v_pk_add_f32 v[218:219], v[218:219], s[100:101] op_sel_hi:[1,0]
	v_rcp_f32_e32 v126, v212
	v_rcp_f32_e32 v127, v213
	v_rcp_f32_e32 v124, v214
	v_rcp_f32_e32 v125, v215
	v_rcp_f32_e32 v122, v216
	v_rcp_f32_e32 v123, v217
	v_rcp_f32_e32 v120, v218
	v_rcp_f32_e32 v121, v219
	s_ashr_i32 s69, s68, 31
	v_cvt_pk_bf16_f32 v156, v122, v123
	v_cvt_pk_bf16_f32 v157, v120, v121
	v_lshl_add_u64 v[120:121], s[42:43], 0, v[150:151]
	v_lshl_add_u64 v[122:123], s[68:69], 0, v[138:139]
	v_cvt_pk_bf16_f32 v158, v126, v127
	v_cvt_pk_bf16_f32 v159, v124, v125
	v_lshl_add_u64 v[120:121], v[122:123], 1, v[120:121]
	global_store_dwordx4 v[120:121], v[156:159], off offset:-1024 nt
	v_add_u32_e32 v120, s21, v165
	v_and_b32_e32 v124, 0xfffff800, v120
	s_or_b32 s21, s57, 16
	v_or_b32_e32 v112, s21, v162
	v_ashrrev_i32_e32 v113, 31, v112
	v_lshlrev_b64 v[114:115], 10, v[112:113]
	v_mad_i64_i32 v[112:113], s[74:75], v112, s10, 0
	v_pk_add_f32 v[212:213], v[104:105], v[200:201]
	v_pk_add_f32 v[214:215], v[106:107], v[202:203]
	v_pk_add_f32 v[216:217], v[108:109], v[196:197]
	v_pk_add_f32 v[218:219], v[110:111], v[198:199]
	v_pk_mul_f32 v[212:213], v[212:213], s[98:99] op_sel_hi:[1,0]
	v_pk_mul_f32 v[214:215], v[214:215], s[98:99] op_sel_hi:[1,0]
	v_pk_mul_f32 v[216:217], v[216:217], s[98:99] op_sel_hi:[1,0]
	v_pk_mul_f32 v[218:219], v[218:219], s[98:99] op_sel_hi:[1,0]
	v_exp_f32_e32 v212, v212
	v_exp_f32_e32 v213, v213
	v_exp_f32_e32 v214, v214
	v_exp_f32_e32 v215, v215
	v_exp_f32_e32 v216, v216
	v_exp_f32_e32 v217, v217
	v_exp_f32_e32 v218, v218
	v_exp_f32_e32 v219, v219
	v_pk_add_f32 v[212:213], v[212:213], s[100:101] op_sel_hi:[1,0]
	v_pk_add_f32 v[214:215], v[214:215], s[100:101] op_sel_hi:[1,0]
	v_pk_add_f32 v[216:217], v[216:217], s[100:101] op_sel_hi:[1,0]
	v_pk_add_f32 v[218:219], v[218:219], s[100:101] op_sel_hi:[1,0]
	v_rcp_f32_e32 v122, v212
	v_rcp_f32_e32 v123, v213
	v_rcp_f32_e32 v120, v214
	v_rcp_f32_e32 v121, v215
	v_rcp_f32_e32 v118, v216
; #define GAS __attribute__((address_space(1)))
; __device__ __forceinline__ float sigmoidf_(float x) { return frcp(1.f + fexp2(-x * LOG2E)); }
; __device__ __forceinline__ float siluf_(float x) { return x * sigmoidf_(x); }
; __device__ __forceinline__ u32x4 pack8(f32x4 a, f32x4 b) { u32x4 w; w.x = pk2(a[0], a[1]); w.y = pk2(a[2], a[3]); w.z = pk2(b[0], b[1]); w.w = pk2(b[2], b[3]); return w; }
;     __device__ __forceinline__ void operator()(const Unit& u, int row, int col, f32x4 v0, f32x4 v1) const {
;     ...
;             const int pc = pn * 256 - 512 + col;
;             if (pn >= 10) {
;                 const f32x4 b0 = *(const GAS f32x4*)(b_gate + pc - PC_GATE), b1 = *(const GAS f32x4*)(b_gate + pc - PC_GATE + 4);
; #pragma unroll
;                 for (int i = 0; i < 4; ++i) { v0[i] = sigmoidf_(v0[i] + b0[i]); v1[i] = sigmoidf_(v1[i] + b1[i]); }
;             } else if (pn == 8 || pn == 9) {
;                 const float sc = 0.08838834764831845f * LOG2E;
;                 v0 = v0 * sc; v1 = v1 * sc;
;             } else {
; #pragma unroll
;                 for (int i = 0; i < 4; ++i) { v0[i] = siluf_(v0[i]); v1[i] = siluf_(v1[i]); }
;             }
;             __builtin_nontemporal_store(pack8(v0, v1), (GAS u32x4*)(P + (size_t)row * PW + pc));
	v_rcp_f32_e32 v119, v217
	v_rcp_f32_e32 v116, v218
	v_rcp_f32_e32 v117, v219
	s_ashr_i32 s69, s68, 31
	v_cvt_pk_bf16_f32 v150, v118, v119
	v_cvt_pk_bf16_f32 v151, v116, v117
	v_lshl_add_u64 v[116:117], s[42:43], 0, v[112:113]
	v_lshl_add_u64 v[118:119], s[68:69], 0, v[136:137]
	v_cvt_pk_bf16_f32 v152, v122, v123
	v_cvt_pk_bf16_f32 v153, v120, v121
	v_lshl_add_u64 v[116:117], v[118:119], 1, v[116:117]
	global_store_dwordx4 v[116:117], v[150:153], off offset:-1024 nt
	s_ashr_i32 s21, s21, 4
	v_pk_add_f32 v[212:213], v[96:97], v[208:209]
	v_pk_add_f32 v[214:215], v[98:99], v[210:211]
	v_pk_add_f32 v[216:217], v[100:101], v[204:205]
	v_pk_add_f32 v[218:219], v[102:103], v[206:207]
	v_pk_mul_f32 v[212:213], v[212:213], s[98:99] op_sel_hi:[1,0]
	v_pk_mul_f32 v[214:215], v[214:215], s[98:99] op_sel_hi:[1,0]
	v_pk_mul_f32 v[216:217], v[216:217], s[98:99] op_sel_hi:[1,0]
	v_pk_mul_f32 v[218:219], v[218:219], s[98:99] op_sel_hi:[1,0]
	v_exp_f32_e32 v212, v212
	v_exp_f32_e32 v213, v213
	v_exp_f32_e32 v214, v214
	v_exp_f32_e32 v215, v215
	v_exp_f32_e32 v216, v216
	v_exp_f32_e32 v217, v217
	v_exp_f32_e32 v218, v218
	v_exp_f32_e32 v219, v219
	v_pk_add_f32 v[212:213], v[212:213], s[100:101] op_sel_hi:[1,0]
	v_pk_add_f32 v[214:215], v[214:215], s[100:101] op_sel_hi:[1,0]
	v_pk_add_f32 v[216:217], v[216:217], s[100:101] op_sel_hi:[1,0]
	v_pk_add_f32 v[218:219], v[218:219], s[100:101] op_sel_hi:[1,0]
	v_rcp_f32_e32 v110, v212
	v_rcp_f32_e32 v111, v213
	v_rcp_f32_e32 v108, v214
	v_rcp_f32_e32 v109, v215
	v_rcp_f32_e32 v106, v216
	v_rcp_f32_e32 v107, v217
	v_rcp_f32_e32 v104, v218
	v_rcp_f32_e32 v105, v219
	s_ashr_i32 s69, s68, 31
	v_cvt_pk_bf16_f32 v114, v106, v107
	v_cvt_pk_bf16_f32 v115, v104, v105
	v_lshl_add_u64 v[104:105], s[42:43], 0, v[112:113]
	v_lshl_add_u64 v[106:107], s[68:69], 0, v[138:139]
	v_cvt_pk_bf16_f32 v116, v110, v111
	v_cvt_pk_bf16_f32 v117, v108, v109
	v_lshl_add_u64 v[104:105], v[106:107], 1, v[104:105]
	global_store_dwordx4 v[104:105], v[114:117], off offset:-1024 nt
	s_or_b32 s21, s57, 32
	v_or_b32_e32 v96, s21, v162
	v_ashrrev_i32_e32 v97, 31, v96
	v_lshlrev_b64 v[98:99], 10, v[96:97]
	v_mad_i64_i32 v[96:97], s[74:75], v96, s10, 0
	v_pk_add_f32 v[212:213], v[88:89], v[200:201]
	v_pk_add_f32 v[214:215], v[90:91], v[202:203]
	v_pk_add_f32 v[216:217], v[92:93], v[196:197]
	v_pk_add_f32 v[218:219], v[94:95], v[198:199]
	v_pk_mul_f32 v[212:213], v[212:213], s[98:99] op_sel_hi:[1,0]
	v_pk_mul_f32 v[214:215], v[214:215], s[98:99] op_sel_hi:[1,0]
	v_pk_mul_f32 v[216:217], v[216:217], s[98:99] op_sel_hi:[1,0]
	v_pk_mul_f32 v[218:219], v[218:219], s[98:99] op_sel_hi:[1,0]
	v_exp_f32_e32 v212, v212
	v_exp_f32_e32 v213, v213
	v_exp_f32_e32 v214, v214
	v_exp_f32_e32 v215, v215
	v_exp_f32_e32 v216, v216
	v_exp_f32_e32 v217, v217
	v_exp_f32_e32 v218, v218
	v_exp_f32_e32 v219, v219
	v_pk_add_f32 v[212:213], v[212:213], s[100:101] op_sel_hi:[1,0]
	v_pk_add_f32 v[214:215], v[214:215], s[100:101] op_sel_hi:[1,0]
	v_pk_add_f32 v[216:217], v[216:217], s[100:101] op_sel_hi:[1,0]
	v_pk_add_f32 v[218:219], v[218:219], s[100:101] op_sel_hi:[1,0]
	v_rcp_f32_e32 v106, v212
	v_rcp_f32_e32 v107, v213
	v_rcp_f32_e32 v104, v214
	v_rcp_f32_e32 v105, v215
	v_rcp_f32_e32 v102, v216
	v_rcp_f32_e32 v103, v217
	v_rcp_f32_e32 v100, v218
	v_rcp_f32_e32 v101, v219
	s_ashr_i32 s69, s68, 31
	v_cvt_pk_bf16_f32 v108, v102, v103
	v_cvt_pk_bf16_f32 v109, v100, v101
	v_lshl_add_u64 v[100:101], s[42:43], 0, v[96:97]
	v_lshl_add_u64 v[102:103], s[68:69], 0, v[136:137]
	v_cvt_pk_bf16_f32 v110, v106, v107
	v_cvt_pk_bf16_f32 v111, v104, v105
	v_lshl_add_u64 v[100:101], v[102:103], 1, v[100:101]
	global_store_dwordx4 v[100:101], v[108:111], off offset:-1024 nt
	s_ashr_i32 s21, s21, 4
	v_pk_add_f32 v[212:213], v[80:81], v[208:209]
	v_pk_add_f32 v[214:215], v[82:83], v[210:211]
	v_pk_add_f32 v[216:217], v[84:85], v[204:205]
	v_pk_add_f32 v[218:219], v[86:87], v[206:207]
	v_pk_mul_f32 v[212:213], v[212:213], s[98:99] op_sel_hi:[1,0]
	v_pk_mul_f32 v[214:215], v[214:215], s[98:99] op_sel_hi:[1,0]
	v_pk_mul_f32 v[216:217], v[216:217], s[98:99] op_sel_hi:[1,0]
	v_pk_mul_f32 v[218:219], v[218:219], s[98:99] op_sel_hi:[1,0]
	v_exp_f32_e32 v212, v212
	v_exp_f32_e32 v213, v213
	v_exp_f32_e32 v214, v214
	v_exp_f32_e32 v215, v215
	v_exp_f32_e32 v216, v216
	v_exp_f32_e32 v217, v217
	v_exp_f32_e32 v218, v218
	v_exp_f32_e32 v219, v219
	v_pk_add_f32 v[212:213], v[212:213], s[100:101] op_sel_hi:[1,0]
	v_pk_add_f32 v[214:215], v[214:215], s[100:101] op_sel_hi:[1,0]
	v_pk_add_f32 v[216:217], v[216:217], s[100:101] op_sel_hi:[1,0]
	v_pk_add_f32 v[218:219], v[218:219], s[100:101] op_sel_hi:[1,0]
	v_rcp_f32_e32 v94, v212
	v_rcp_f32_e32 v95, v213
	v_rcp_f32_e32 v92, v214
	v_rcp_f32_e32 v93, v215
	v_rcp_f32_e32 v90, v216
	v_rcp_f32_e32 v91, v217
	v_rcp_f32_e32 v88, v218
	v_rcp_f32_e32 v89, v219
	s_ashr_i32 s69, s68, 31
	v_cvt_pk_bf16_f32 v98, v90, v91
	v_cvt_pk_bf16_f32 v99, v88, v89
	v_lshl_add_u64 v[88:89], s[42:43], 0, v[96:97]
	v_lshl_add_u64 v[90:91], s[68:69], 0, v[138:139]
	v_cvt_pk_bf16_f32 v100, v94, v95
	v_cvt_pk_bf16_f32 v101, v92, v93
	v_lshl_add_u64 v[88:89], v[90:91], 1, v[88:89]
	global_store_dwordx4 v[88:89], v[98:101], off offset:-1024 nt
	s_or_b32 s21, s57, 48
	v_or_b32_e32 v80, s21, v162
	v_ashrrev_i32_e32 v81, 31, v80
	v_lshlrev_b64 v[82:83], 10, v[80:81]
	v_mad_i64_i32 v[80:81], s[74:75], v80, s10, 0
	v_pk_add_f32 v[212:213], v[72:73], v[200:201]
	v_pk_add_f32 v[214:215], v[74:75], v[202:203]
	v_pk_add_f32 v[216:217], v[76:77], v[196:197]
	v_pk_add_f32 v[218:219], v[78:79], v[198:199]
	v_pk_mul_f32 v[212:213], v[212:213], s[98:99] op_sel_hi:[1,0]
	v_pk_mul_f32 v[214:215], v[214:215], s[98:99] op_sel_hi:[1,0]
; #define GAS __attribute__((address_space(1)))
; __device__ __forceinline__ float sigmoidf_(float x) { return frcp(1.f + fexp2(-x * LOG2E)); }
; __device__ __forceinline__ float siluf_(float x) { return x * sigmoidf_(x); }
; __device__ __forceinline__ u32x4 pack8(f32x4 a, f32x4 b) { u32x4 w; w.x = pk2(a[0], a[1]); w.y = pk2(a[2], a[3]); w.z = pk2(b[0], b[1]); w.w = pk2(b[2], b[3]); return w; }
;     __device__ __forceinline__ void operator()(const Unit& u, int row, int col, f32x4 v0, f32x4 v1) const {
;     ...
;             const int pc = pn * 256 - 512 + col;
;             if (pn >= 10) {
;                 const f32x4 b0 = *(const GAS f32x4*)(b_gate + pc - PC_GATE), b1 = *(const GAS f32x4*)(b_gate + pc - PC_GATE + 4);
; #pragma unroll
;                 for (int i = 0; i < 4; ++i) { v0[i] = sigmoidf_(v0[i] + b0[i]); v1[i] = sigmoidf_(v1[i] + b1[i]); }
;             } else if (pn == 8 || pn == 9) {
;                 const float sc = 0.08838834764831845f * LOG2E;
;                 v0 = v0 * sc; v1 = v1 * sc;
;             } else {
; #pragma unroll
;                 for (int i = 0; i < 4; ++i) { v0[i] = siluf_(v0[i]); v1[i] = siluf_(v1[i]); }
;             }
;             __builtin_nontemporal_store(pack8(v0, v1), (GAS u32x4*)(P + (size_t)row * PW + pc));
	v_pk_mul_f32 v[216:217], v[216:217], s[98:99] op_sel_hi:[1,0]
	v_pk_mul_f32 v[218:219], v[218:219], s[98:99] op_sel_hi:[1,0]
	v_exp_f32_e32 v212, v212
	v_exp_f32_e32 v213, v213
	v_exp_f32_e32 v214, v214
	v_exp_f32_e32 v215, v215
	v_exp_f32_e32 v216, v216
	v_exp_f32_e32 v217, v217
	v_exp_f32_e32 v218, v218
	v_exp_f32_e32 v219, v219
	v_pk_add_f32 v[212:213], v[212:213], s[100:101] op_sel_hi:[1,0]
	v_pk_add_f32 v[214:215], v[214:215], s[100:101] op_sel_hi:[1,0]
	v_pk_add_f32 v[216:217], v[216:217], s[100:101] op_sel_hi:[1,0]
	v_pk_add_f32 v[218:219], v[218:219], s[100:101] op_sel_hi:[1,0]
	v_rcp_f32_e32 v90, v212
	v_rcp_f32_e32 v91, v213
	v_rcp_f32_e32 v88, v214
	v_rcp_f32_e32 v89, v215
	v_rcp_f32_e32 v86, v216
	v_rcp_f32_e32 v87, v217
	v_rcp_f32_e32 v84, v218
	v_rcp_f32_e32 v85, v219
	s_ashr_i32 s69, s68, 31
	v_cvt_pk_bf16_f32 v92, v86, v87
	v_cvt_pk_bf16_f32 v93, v84, v85
	v_lshl_add_u64 v[84:85], s[42:43], 0, v[80:81]
	v_lshl_add_u64 v[86:87], s[68:69], 0, v[136:137]
	v_cvt_pk_bf16_f32 v94, v90, v91
	v_cvt_pk_bf16_f32 v95, v88, v89
	v_lshl_add_u64 v[84:85], v[86:87], 1, v[84:85]
	global_store_dwordx4 v[84:85], v[92:95], off offset:-1024 nt
	s_ashr_i32 s21, s21, 4
	v_pk_add_f32 v[212:213], v[64:65], v[208:209]
	v_pk_add_f32 v[214:215], v[66:67], v[210:211]
	v_pk_add_f32 v[216:217], v[68:69], v[204:205]
	v_pk_add_f32 v[218:219], v[70:71], v[206:207]
	v_pk_mul_f32 v[212:213], v[212:213], s[98:99] op_sel_hi:[1,0]
	v_pk_mul_f32 v[214:215], v[214:215], s[98:99] op_sel_hi:[1,0]
	v_pk_mul_f32 v[216:217], v[216:217], s[98:99] op_sel_hi:[1,0]
	v_pk_mul_f32 v[218:219], v[218:219], s[98:99] op_sel_hi:[1,0]
	v_exp_f32_e32 v212, v212
	v_exp_f32_e32 v213, v213
	v_exp_f32_e32 v214, v214
	v_exp_f32_e32 v215, v215
	v_exp_f32_e32 v216, v216
	v_exp_f32_e32 v217, v217
	v_exp_f32_e32 v218, v218
	v_exp_f32_e32 v219, v219
	v_pk_add_f32 v[212:213], v[212:213], s[100:101] op_sel_hi:[1,0]
	v_pk_add_f32 v[214:215], v[214:215], s[100:101] op_sel_hi:[1,0]
	v_pk_add_f32 v[216:217], v[216:217], s[100:101] op_sel_hi:[1,0]
	v_pk_add_f32 v[218:219], v[218:219], s[100:101] op_sel_hi:[1,0]
	v_rcp_f32_e32 v78, v212
	v_rcp_f32_e32 v79, v213
	v_rcp_f32_e32 v76, v214
	v_rcp_f32_e32 v77, v215
	v_rcp_f32_e32 v74, v216
	v_rcp_f32_e32 v75, v217
	v_rcp_f32_e32 v72, v218
	v_rcp_f32_e32 v73, v219
	s_ashr_i32 s69, s68, 31
	v_cvt_pk_bf16_f32 v82, v74, v75
	v_cvt_pk_bf16_f32 v83, v72, v73
	v_lshl_add_u64 v[72:73], s[42:43], 0, v[80:81]
	v_lshl_add_u64 v[74:75], s[68:69], 0, v[138:139]
	v_cvt_pk_bf16_f32 v84, v78, v79
	v_cvt_pk_bf16_f32 v85, v76, v77
	v_lshl_add_u64 v[72:73], v[74:75], 1, v[72:73]
	global_store_dwordx4 v[72:73], v[82:85], off offset:-1024 nt
	s_add_i32 s21, s57, 0x80
	v_or_b32_e32 v64, s21, v162
	v_ashrrev_i32_e32 v65, 31, v64
	v_lshlrev_b64 v[66:67], 10, v[64:65]
	v_mad_i64_i32 v[64:65], s[74:75], v64, s10, 0
	v_pk_add_f32 v[212:213], v[56:57], v[200:201]
	v_pk_add_f32 v[214:215], v[58:59], v[202:203]
	v_pk_add_f32 v[216:217], v[60:61], v[196:197]
	v_pk_add_f32 v[218:219], v[62:63], v[198:199]
	v_pk_mul_f32 v[212:213], v[212:213], s[98:99] op_sel_hi:[1,0]
	v_pk_mul_f32 v[214:215], v[214:215], s[98:99] op_sel_hi:[1,0]
	v_pk_mul_f32 v[216:217], v[216:217], s[98:99] op_sel_hi:[1,0]
	v_pk_mul_f32 v[218:219], v[218:219], s[98:99] op_sel_hi:[1,0]
	v_exp_f32_e32 v212, v212
	v_exp_f32_e32 v213, v213
	v_exp_f32_e32 v214, v214
	v_exp_f32_e32 v215, v215
	v_exp_f32_e32 v216, v216
	v_exp_f32_e32 v217, v217
	v_exp_f32_e32 v218, v218
	v_exp_f32_e32 v219, v219
	v_pk_add_f32 v[212:213], v[212:213], s[100:101] op_sel_hi:[1,0]
	v_pk_add_f32 v[214:215], v[214:215], s[100:101] op_sel_hi:[1,0]
	v_pk_add_f32 v[216:217], v[216:217], s[100:101] op_sel_hi:[1,0]
	v_pk_add_f32 v[218:219], v[218:219], s[100:101] op_sel_hi:[1,0]
	v_rcp_f32_e32 v74, v212
	v_rcp_f32_e32 v75, v213
	v_rcp_f32_e32 v72, v214
	v_rcp_f32_e32 v73, v215
	v_rcp_f32_e32 v70, v216
	v_rcp_f32_e32 v71, v217
	v_rcp_f32_e32 v68, v218
	v_rcp_f32_e32 v69, v219
	s_ashr_i32 s69, s68, 31
	v_cvt_pk_bf16_f32 v76, v70, v71
	v_cvt_pk_bf16_f32 v77, v68, v69
	v_lshl_add_u64 v[68:69], s[42:43], 0, v[64:65]
	v_lshl_add_u64 v[70:71], s[68:69], 0, v[136:137]
	v_cvt_pk_bf16_f32 v78, v74, v75
	v_cvt_pk_bf16_f32 v79, v72, v73
	v_lshl_add_u64 v[68:69], v[70:71], 1, v[68:69]
	global_store_dwordx4 v[68:69], v[76:79], off offset:-1024 nt
	s_ashr_i32 s21, s21, 4
	v_pk_add_f32 v[212:213], v[48:49], v[208:209]
	v_pk_add_f32 v[214:215], v[50:51], v[210:211]
	v_pk_add_f32 v[216:217], v[52:53], v[204:205]
	v_pk_add_f32 v[218:219], v[54:55], v[206:207]
	v_pk_mul_f32 v[212:213], v[212:213], s[98:99] op_sel_hi:[1,0]
	v_pk_mul_f32 v[214:215], v[214:215], s[98:99] op_sel_hi:[1,0]
	v_pk_mul_f32 v[216:217], v[216:217], s[98:99] op_sel_hi:[1,0]
	v_pk_mul_f32 v[218:219], v[218:219], s[98:99] op_sel_hi:[1,0]
	v_exp_f32_e32 v212, v212
	v_exp_f32_e32 v213, v213
	v_exp_f32_e32 v214, v214
	v_exp_f32_e32 v215, v215
	v_exp_f32_e32 v216, v216
	v_exp_f32_e32 v217, v217
	v_exp_f32_e32 v218, v218
	v_exp_f32_e32 v219, v219
	v_pk_add_f32 v[212:213], v[212:213], s[100:101] op_sel_hi:[1,0]
	v_pk_add_f32 v[214:215], v[214:215], s[100:101] op_sel_hi:[1,0]
	v_pk_add_f32 v[216:217], v[216:217], s[100:101] op_sel_hi:[1,0]
	v_pk_add_f32 v[218:219], v[218:219], s[100:101] op_sel_hi:[1,0]
	v_rcp_f32_e32 v62, v212
	v_rcp_f32_e32 v63, v213
	v_rcp_f32_e32 v60, v214
	v_rcp_f32_e32 v61, v215
	v_rcp_f32_e32 v58, v216
	v_rcp_f32_e32 v59, v217
	v_rcp_f32_e32 v56, v218
	v_rcp_f32_e32 v57, v219
	s_ashr_i32 s69, s68, 31
	v_cvt_pk_bf16_f32 v66, v58, v59
	v_cvt_pk_bf16_f32 v67, v56, v57
	v_lshl_add_u64 v[56:57], s[42:43], 0, v[64:65]
	v_lshl_add_u64 v[58:59], s[68:69], 0, v[138:139]
	v_cvt_pk_bf16_f32 v68, v62, v63
; #define GAS __attribute__((address_space(1)))
; __device__ __forceinline__ float sigmoidf_(float x) { return frcp(1.f + fexp2(-x * LOG2E)); }
; __device__ __forceinline__ float siluf_(float x) { return x * sigmoidf_(x); }
; __device__ __forceinline__ u32x4 pack8(f32x4 a, f32x4 b) { u32x4 w; w.x = pk2(a[0], a[1]); w.y = pk2(a[2], a[3]); w.z = pk2(b[0], b[1]); w.w = pk2(b[2], b[3]); return w; }
;     __device__ __forceinline__ void operator()(const Unit& u, int row, int col, f32x4 v0, f32x4 v1) const {
;     ...
;             const int pc = pn * 256 - 512 + col;
;             if (pn >= 10) {
;                 const f32x4 b0 = *(const GAS f32x4*)(b_gate + pc - PC_GATE), b1 = *(const GAS f32x4*)(b_gate + pc - PC_GATE + 4);
; #pragma unroll
;                 for (int i = 0; i < 4; ++i) { v0[i] = sigmoidf_(v0[i] + b0[i]); v1[i] = sigmoidf_(v1[i] + b1[i]); }
;             } else if (pn == 8 || pn == 9) {
;                 const float sc = 0.08838834764831845f * LOG2E;
;                 v0 = v0 * sc; v1 = v1 * sc;
;             } else {
; #pragma unroll
;                 for (int i = 0; i < 4; ++i) { v0[i] = siluf_(v0[i]); v1[i] = siluf_(v1[i]); }
;             }
;             __builtin_nontemporal_store(pack8(v0, v1), (GAS u32x4*)(P + (size_t)row * PW + pc));
	v_cvt_pk_bf16_f32 v69, v60, v61
	v_lshl_add_u64 v[56:57], v[58:59], 1, v[56:57]
	global_store_dwordx4 v[56:57], v[66:69], off offset:-1024 nt
	s_add_i32 s21, s57, 0x90
	v_or_b32_e32 v48, s21, v162
	v_ashrrev_i32_e32 v49, 31, v48
	v_lshlrev_b64 v[50:51], 10, v[48:49]
	v_mad_i64_i32 v[48:49], s[74:75], v48, s10, 0
	v_pk_add_f32 v[212:213], v[40:41], v[200:201]
	v_pk_add_f32 v[214:215], v[42:43], v[202:203]
	v_pk_add_f32 v[216:217], v[44:45], v[196:197]
	v_pk_add_f32 v[218:219], v[46:47], v[198:199]
	v_pk_mul_f32 v[212:213], v[212:213], s[98:99] op_sel_hi:[1,0]
	v_pk_mul_f32 v[214:215], v[214:215], s[98:99] op_sel_hi:[1,0]
	v_pk_mul_f32 v[216:217], v[216:217], s[98:99] op_sel_hi:[1,0]
	v_pk_mul_f32 v[218:219], v[218:219], s[98:99] op_sel_hi:[1,0]
	v_exp_f32_e32 v212, v212
	v_exp_f32_e32 v213, v213
	v_exp_f32_e32 v214, v214
	v_exp_f32_e32 v215, v215
	v_exp_f32_e32 v216, v216
	v_exp_f32_e32 v217, v217
	v_exp_f32_e32 v218, v218
	v_exp_f32_e32 v219, v219
	v_pk_add_f32 v[212:213], v[212:213], s[100:101] op_sel_hi:[1,0]
	v_pk_add_f32 v[214:215], v[214:215], s[100:101] op_sel_hi:[1,0]
	v_pk_add_f32 v[216:217], v[216:217], s[100:101] op_sel_hi:[1,0]
	v_pk_add_f32 v[218:219], v[218:219], s[100:101] op_sel_hi:[1,0]
	v_rcp_f32_e32 v58, v212
	v_rcp_f32_e32 v59, v213
	v_rcp_f32_e32 v56, v214
	v_rcp_f32_e32 v57, v215
	v_rcp_f32_e32 v54, v216
	v_rcp_f32_e32 v55, v217
	v_rcp_f32_e32 v52, v218
	v_rcp_f32_e32 v53, v219
	s_ashr_i32 s69, s68, 31
	v_cvt_pk_bf16_f32 v60, v54, v55
	v_cvt_pk_bf16_f32 v61, v52, v53
	v_lshl_add_u64 v[52:53], s[42:43], 0, v[48:49]
	v_lshl_add_u64 v[54:55], s[68:69], 0, v[136:137]
	v_cvt_pk_bf16_f32 v62, v58, v59
	v_cvt_pk_bf16_f32 v63, v56, v57
	v_lshl_add_u64 v[52:53], v[54:55], 1, v[52:53]
	global_store_dwordx4 v[52:53], v[60:63], off offset:-1024 nt
	s_ashr_i32 s21, s21, 4
	v_pk_add_f32 v[212:213], v[32:33], v[208:209]
	v_pk_add_f32 v[214:215], v[34:35], v[210:211]
	v_pk_add_f32 v[216:217], v[36:37], v[204:205]
	v_pk_add_f32 v[218:219], v[38:39], v[206:207]
	v_pk_mul_f32 v[212:213], v[212:213], s[98:99] op_sel_hi:[1,0]
	v_pk_mul_f32 v[214:215], v[214:215], s[98:99] op_sel_hi:[1,0]
	v_pk_mul_f32 v[216:217], v[216:217], s[98:99] op_sel_hi:[1,0]
	v_pk_mul_f32 v[218:219], v[218:219], s[98:99] op_sel_hi:[1,0]
	v_exp_f32_e32 v212, v212
	v_exp_f32_e32 v213, v213
	v_exp_f32_e32 v214, v214
	v_exp_f32_e32 v215, v215
	v_exp_f32_e32 v216, v216
	v_exp_f32_e32 v217, v217
	v_exp_f32_e32 v218, v218
	v_exp_f32_e32 v219, v219
	v_pk_add_f32 v[212:213], v[212:213], s[100:101] op_sel_hi:[1,0]
	v_pk_add_f32 v[214:215], v[214:215], s[100:101] op_sel_hi:[1,0]
	v_pk_add_f32 v[216:217], v[216:217], s[100:101] op_sel_hi:[1,0]
	v_pk_add_f32 v[218:219], v[218:219], s[100:101] op_sel_hi:[1,0]
	v_rcp_f32_e32 v46, v212
	v_rcp_f32_e32 v47, v213
	v_rcp_f32_e32 v44, v214
	v_rcp_f32_e32 v45, v215
	v_rcp_f32_e32 v42, v216
	v_rcp_f32_e32 v43, v217
	v_rcp_f32_e32 v40, v218
	v_rcp_f32_e32 v41, v219
	s_ashr_i32 s69, s68, 31
	v_cvt_pk_bf16_f32 v50, v42, v43
	v_cvt_pk_bf16_f32 v51, v40, v41
	v_lshl_add_u64 v[40:41], s[42:43], 0, v[48:49]
	v_lshl_add_u64 v[42:43], s[68:69], 0, v[138:139]
	v_cvt_pk_bf16_f32 v52, v46, v47
	v_cvt_pk_bf16_f32 v53, v44, v45
	v_lshl_add_u64 v[40:41], v[42:43], 1, v[40:41]
	global_store_dwordx4 v[40:41], v[50:53], off offset:-1024 nt
	s_add_i32 s21, s57, 0xa0
	v_or_b32_e32 v32, s21, v162
	v_ashrrev_i32_e32 v33, 31, v32
	v_lshlrev_b64 v[34:35], 10, v[32:33]
	v_mad_i64_i32 v[32:33], s[74:75], v32, s10, 0
	v_pk_add_f32 v[212:213], v[24:25], v[200:201]
	v_pk_add_f32 v[214:215], v[26:27], v[202:203]
	v_pk_add_f32 v[216:217], v[28:29], v[196:197]
	v_pk_add_f32 v[218:219], v[30:31], v[198:199]
	v_pk_mul_f32 v[212:213], v[212:213], s[98:99] op_sel_hi:[1,0]
	v_pk_mul_f32 v[214:215], v[214:215], s[98:99] op_sel_hi:[1,0]
	v_pk_mul_f32 v[216:217], v[216:217], s[98:99] op_sel_hi:[1,0]
	v_pk_mul_f32 v[218:219], v[218:219], s[98:99] op_sel_hi:[1,0]
	v_exp_f32_e32 v212, v212
	v_exp_f32_e32 v213, v213
	v_exp_f32_e32 v214, v214
	v_exp_f32_e32 v215, v215
	v_exp_f32_e32 v216, v216
	v_exp_f32_e32 v217, v217
	v_exp_f32_e32 v218, v218
	v_exp_f32_e32 v219, v219
	v_pk_add_f32 v[212:213], v[212:213], s[100:101] op_sel_hi:[1,0]
	v_pk_add_f32 v[214:215], v[214:215], s[100:101] op_sel_hi:[1,0]
	v_pk_add_f32 v[216:217], v[216:217], s[100:101] op_sel_hi:[1,0]
	v_pk_add_f32 v[218:219], v[218:219], s[100:101] op_sel_hi:[1,0]
	v_rcp_f32_e32 v42, v212
	v_rcp_f32_e32 v43, v213
	v_rcp_f32_e32 v40, v214
	v_rcp_f32_e32 v41, v215
	v_rcp_f32_e32 v38, v216
	v_rcp_f32_e32 v39, v217
	v_rcp_f32_e32 v36, v218
	v_rcp_f32_e32 v37, v219
	s_ashr_i32 s69, s68, 31
	v_cvt_pk_bf16_f32 v44, v38, v39
	v_cvt_pk_bf16_f32 v45, v36, v37
	v_lshl_add_u64 v[36:37], s[42:43], 0, v[32:33]
	v_lshl_add_u64 v[38:39], s[68:69], 0, v[136:137]
	v_cvt_pk_bf16_f32 v46, v42, v43
	v_cvt_pk_bf16_f32 v47, v40, v41
	v_lshl_add_u64 v[36:37], v[38:39], 1, v[36:37]
	global_store_dwordx4 v[36:37], v[44:47], off offset:-1024 nt
	s_ashr_i32 s21, s21, 4
	v_pk_add_f32 v[212:213], v[16:17], v[208:209]
	v_pk_add_f32 v[214:215], v[18:19], v[210:211]
	v_pk_add_f32 v[216:217], v[20:21], v[204:205]
	v_pk_add_f32 v[218:219], v[22:23], v[206:207]
	v_pk_mul_f32 v[212:213], v[212:213], s[98:99] op_sel_hi:[1,0]
	v_pk_mul_f32 v[214:215], v[214:215], s[98:99] op_sel_hi:[1,0]
	v_pk_mul_f32 v[216:217], v[216:217], s[98:99] op_sel_hi:[1,0]
	v_pk_mul_f32 v[218:219], v[218:219], s[98:99] op_sel_hi:[1,0]
	v_exp_f32_e32 v212, v212
	v_exp_f32_e32 v213, v213
	v_exp_f32_e32 v214, v214
	v_exp_f32_e32 v215, v215
	v_exp_f32_e32 v216, v216
	v_exp_f32_e32 v217, v217
	v_exp_f32_e32 v218, v218
	v_exp_f32_e32 v219, v219
	v_pk_add_f32 v[212:213], v[212:213], s[100:101] op_sel_hi:[1,0]
; #define GAS __attribute__((address_space(1)))
; __device__ __forceinline__ float sigmoidf_(float x) { return frcp(1.f + fexp2(-x * LOG2E)); }
; __device__ __forceinline__ float siluf_(float x) { return x * sigmoidf_(x); }
; __device__ __forceinline__ u32x4 pack8(f32x4 a, f32x4 b) { u32x4 w; w.x = pk2(a[0], a[1]); w.y = pk2(a[2], a[3]); w.z = pk2(b[0], b[1]); w.w = pk2(b[2], b[3]); return w; }
;     __device__ __forceinline__ void operator()(const Unit& u, int row, int col, f32x4 v0, f32x4 v1) const {
;     ...
;             const int pc = pn * 256 - 512 + col;
;             if (pn >= 10) {
;                 const f32x4 b0 = *(const GAS f32x4*)(b_gate + pc - PC_GATE), b1 = *(const GAS f32x4*)(b_gate + pc - PC_GATE + 4);
; #pragma unroll
;                 for (int i = 0; i < 4; ++i) { v0[i] = sigmoidf_(v0[i] + b0[i]); v1[i] = sigmoidf_(v1[i] + b1[i]); }
;             } else if (pn == 8 || pn == 9) {
;                 const float sc = 0.08838834764831845f * LOG2E;
;                 v0 = v0 * sc; v1 = v1 * sc;
;             } else {
; #pragma unroll
;                 for (int i = 0; i < 4; ++i) { v0[i] = siluf_(v0[i]); v1[i] = siluf_(v1[i]); }
;             }
;             __builtin_nontemporal_store(pack8(v0, v1), (GAS u32x4*)(P + (size_t)row * PW + pc));
;         } else {
;             *(GAS u32x4*)(CQR + (size_t)row * 512 + (pn - 22) * 256 + col) = pack8(v0, v1);
	v_pk_add_f32 v[214:215], v[214:215], s[100:101] op_sel_hi:[1,0]
	v_pk_add_f32 v[216:217], v[216:217], s[100:101] op_sel_hi:[1,0]
	v_pk_add_f32 v[218:219], v[218:219], s[100:101] op_sel_hi:[1,0]
	v_rcp_f32_e32 v30, v212
	v_rcp_f32_e32 v31, v213
	v_rcp_f32_e32 v28, v214
	v_rcp_f32_e32 v29, v215
	v_rcp_f32_e32 v26, v216
	v_rcp_f32_e32 v27, v217
	v_rcp_f32_e32 v24, v218
	v_rcp_f32_e32 v25, v219
	s_ashr_i32 s69, s68, 31
	v_cvt_pk_bf16_f32 v34, v26, v27
	v_cvt_pk_bf16_f32 v35, v24, v25
	v_lshl_add_u64 v[24:25], s[42:43], 0, v[32:33]
	v_lshl_add_u64 v[26:27], s[68:69], 0, v[138:139]
	v_cvt_pk_bf16_f32 v36, v30, v31
	v_cvt_pk_bf16_f32 v37, v28, v29
	v_lshl_add_u64 v[24:25], v[26:27], 1, v[24:25]
	global_store_dwordx4 v[24:25], v[34:37], off offset:-1024 nt
	s_addk_i32 s57, 0xb0
	v_or_b32_e32 v16, s57, v162
	v_ashrrev_i32_e32 v17, 31, v16
	v_lshlrev_b64 v[18:19], 10, v[16:17]
	v_mad_i64_i32 v[16:17], s[74:75], v16, s10, 0
	v_pk_add_f32 v[212:213], v[8:9], v[200:201]
	v_pk_add_f32 v[214:215], v[10:11], v[202:203]
	v_pk_add_f32 v[216:217], v[12:13], v[196:197]
	v_pk_add_f32 v[218:219], v[14:15], v[198:199]
	v_pk_mul_f32 v[212:213], v[212:213], s[98:99] op_sel_hi:[1,0]
	v_pk_mul_f32 v[214:215], v[214:215], s[98:99] op_sel_hi:[1,0]
	v_pk_mul_f32 v[216:217], v[216:217], s[98:99] op_sel_hi:[1,0]
	v_pk_mul_f32 v[218:219], v[218:219], s[98:99] op_sel_hi:[1,0]
	v_exp_f32_e32 v212, v212
	v_exp_f32_e32 v213, v213
	v_exp_f32_e32 v214, v214
	v_exp_f32_e32 v215, v215
	v_exp_f32_e32 v216, v216
	v_exp_f32_e32 v217, v217
	v_exp_f32_e32 v218, v218
	v_exp_f32_e32 v219, v219
	v_pk_add_f32 v[212:213], v[212:213], s[100:101] op_sel_hi:[1,0]
	v_pk_add_f32 v[214:215], v[214:215], s[100:101] op_sel_hi:[1,0]
	v_pk_add_f32 v[216:217], v[216:217], s[100:101] op_sel_hi:[1,0]
	v_pk_add_f32 v[218:219], v[218:219], s[100:101] op_sel_hi:[1,0]
	v_rcp_f32_e32 v26, v212
	v_rcp_f32_e32 v27, v213
	v_rcp_f32_e32 v24, v214
	v_rcp_f32_e32 v25, v215
	v_rcp_f32_e32 v22, v216
	v_rcp_f32_e32 v23, v217
	v_rcp_f32_e32 v20, v218
	v_rcp_f32_e32 v21, v219
	s_ashr_i32 s69, s68, 31
	v_cvt_pk_bf16_f32 v28, v22, v23
	v_cvt_pk_bf16_f32 v29, v20, v21
	v_lshl_add_u64 v[20:21], s[42:43], 0, v[16:17]
	v_lshl_add_u64 v[22:23], s[68:69], 0, v[136:137]
	v_cvt_pk_bf16_f32 v30, v26, v27
	v_cvt_pk_bf16_f32 v31, v24, v25
	v_lshl_add_u64 v[20:21], v[22:23], 1, v[20:21]
	global_store_dwordx4 v[20:21], v[28:31], off offset:-1024 nt
	s_ashr_i32 s21, s57, 4
	v_pk_add_f32 v[212:213], v[0:1], v[208:209]
	v_pk_add_f32 v[214:215], v[2:3], v[210:211]
	v_pk_add_f32 v[216:217], v[4:5], v[204:205]
	v_pk_add_f32 v[218:219], v[6:7], v[206:207]
	v_pk_mul_f32 v[212:213], v[212:213], s[98:99] op_sel_hi:[1,0]
	v_pk_mul_f32 v[214:215], v[214:215], s[98:99] op_sel_hi:[1,0]
	v_pk_mul_f32 v[216:217], v[216:217], s[98:99] op_sel_hi:[1,0]
	v_pk_mul_f32 v[218:219], v[218:219], s[98:99] op_sel_hi:[1,0]
	v_exp_f32_e32 v212, v212
	v_exp_f32_e32 v213, v213
	v_exp_f32_e32 v214, v214
	v_exp_f32_e32 v215, v215
	v_exp_f32_e32 v216, v216
	v_exp_f32_e32 v217, v217
	v_exp_f32_e32 v218, v218
	v_exp_f32_e32 v219, v219
	v_pk_add_f32 v[212:213], v[212:213], s[100:101] op_sel_hi:[1,0]
	v_pk_add_f32 v[214:215], v[214:215], s[100:101] op_sel_hi:[1,0]
	v_pk_add_f32 v[216:217], v[216:217], s[100:101] op_sel_hi:[1,0]
	v_pk_add_f32 v[218:219], v[218:219], s[100:101] op_sel_hi:[1,0]
	v_rcp_f32_e32 v14, v212
	v_rcp_f32_e32 v15, v213
	v_rcp_f32_e32 v12, v214
	v_rcp_f32_e32 v13, v215
	v_rcp_f32_e32 v10, v216
	v_rcp_f32_e32 v11, v217
	v_rcp_f32_e32 v8, v218
	v_rcp_f32_e32 v9, v219
	s_ashr_i32 s69, s68, 31
	v_cvt_pk_bf16_f32 v18, v10, v11
	v_cvt_pk_bf16_f32 v19, v8, v9
	v_lshl_add_u64 v[8:9], s[42:43], 0, v[16:17]
	v_lshl_add_u64 v[10:11], s[68:69], 0, v[138:139]
	v_cvt_pk_bf16_f32 v20, v14, v15
	v_cvt_pk_bf16_f32 v21, v12, v13
	v_lshl_add_u64 v[8:9], v[10:11], 1, v[8:9]
	global_store_dwordx4 v[8:9], v[18:21], off offset:-1024 nt
	s_andn2_b64 vcc, exec, s[4:5]
	s_mov_b64 s[4:5], -1
	s_cbranch_vccnz .LBB0_178
	s_andn2_b64 vcc, exec, s[40:41]
	s_cbranch_vccnz .LBB0_177
	s_barrier
	s_branch .LBB0_177
.Lfp_cls4:
	s_mov_b32 s98, 0xbfb8aa3b
	s_mov_b32 s100, 1.0
	s_lshl_b32 s57, s6, 8
	s_add_i32 s57, s57, s85
	s_lshl_b32 s68, s76, 8
	s_add_i32 s38, s68, 0xffffea00
	v_or_b32_e32 v150, s57, v162
	s_and_b32 s8, s76, 14
	v_ashrrev_i32_e32 v151, 31, v150
	v_lshlrev_b64 v[152:153], 10, v[150:151]
	v_mad_i64_i32 v[150:151], s[8:9], v150, s10, 0
	v_lshl_add_u64 v[158:159], s[44:45], 0, v[152:153]
	v_lshl_add_u64 v[158:159], s[38:39], 1, v[158:159]
	v_cvt_pk_bf16_f32 v154, v120, v121
	v_cvt_pk_bf16_f32 v155, v122, v123
	v_cvt_pk_bf16_f32 v156, v124, v125
	v_cvt_pk_bf16_f32 v157, v126, v127
	v_lshl_add_u64 v[158:159], v[136:137], 1, v[158:159]
	global_store_dwordx4 v[158:159], v[154:157], off
	s_nop 1
	s_lshl_b32 s21, s76, 15
	v_add_u32_e32 v154, s21, v164
	s_ashr_i32 s59, s57, 4
	v_and_b32_e32 v154, 0xfffff800, v154
	s_nop 1
	v_lshl_add_u64 v[124:125], s[44:45], 0, v[152:153]
	v_lshl_add_u64 v[124:125], s[38:39], 1, v[124:125]
	v_cvt_pk_bf16_f32 v120, v116, v117
	v_cvt_pk_bf16_f32 v121, v118, v119
	v_cvt_pk_bf16_f32 v122, v112, v113
	v_cvt_pk_bf16_f32 v123, v114, v115
	v_lshl_add_u64 v[124:125], v[136:137], 1, v[124:125]
	global_store_dwordx4 v[124:125], v[120:123], off offset:256
	s_nop 1
	v_add_u32_e32 v120, s21, v165
	v_and_b32_e32 v124, 0xfffff800, v120
	s_or_b32 s21, s57, 16
	v_or_b32_e32 v112, s21, v162
	v_ashrrev_i32_e32 v113, 31, v112
	v_lshlrev_b64 v[114:115], 10, v[112:113]
	v_mad_i64_i32 v[112:113], s[74:75], v112, s10, 0
	v_lshl_add_u64 v[120:121], s[44:45], 0, v[114:115]
	v_lshl_add_u64 v[120:121], s[38:39], 1, v[120:121]
	v_cvt_pk_bf16_f32 v116, v108, v109
; #define GAS __attribute__((address_space(1)))
; __device__ __forceinline__ u32x4 pack8(f32x4 a, f32x4 b) { u32x4 w; w.x = pk2(a[0], a[1]); w.y = pk2(a[2], a[3]); w.z = pk2(b[0], b[1]); w.w = pk2(b[2], b[3]); return w; }
;     __device__ __forceinline__ void operator()(const f32x4 (&acc)[2][2][4][2], const Unit& u, int wr, int wc, int fr, int fq) const {
;     ...
;             for (int m = 0; m < 4; ++m) {
;                 const int row = u.pm * BM + ai * HALF + wr * 64 + m * 16 + fr;
; #pragma unroll
;                 for (int bj = 0; bj < 2; ++bj) f(u, row, bj * HALF + wc * 32 + 8 * fq, acc[ai][bj][m][0], acc[ai][bj][m][1]);
;     __device__ __forceinline__ void operator()(const Unit& u, int row, int col, f32x4 v0, f32x4 v1) const {
;     ...
;         } else {
;             *(GAS u32x4*)(CQR + (size_t)row * 512 + (pn - 22) * 256 + col) = pack8(v0, v1);
	v_cvt_pk_bf16_f32 v117, v110, v111
	v_cvt_pk_bf16_f32 v118, v104, v105
	v_cvt_pk_bf16_f32 v119, v106, v107
	v_lshl_add_u64 v[120:121], v[136:137], 1, v[120:121]
	global_store_dwordx4 v[120:121], v[116:119], off
	s_ashr_i32 s21, s21, 4
	v_lshl_add_u64 v[108:109], s[44:45], 0, v[114:115]
	v_lshl_add_u64 v[108:109], s[38:39], 1, v[108:109]
	v_cvt_pk_bf16_f32 v104, v100, v101
	v_cvt_pk_bf16_f32 v105, v102, v103
	v_cvt_pk_bf16_f32 v106, v96, v97
	v_cvt_pk_bf16_f32 v107, v98, v99
	v_lshl_add_u64 v[108:109], v[136:137], 1, v[108:109]
	global_store_dwordx4 v[108:109], v[104:107], off offset:256
	s_or_b32 s21, s57, 32
	v_or_b32_e32 v96, s21, v162
	v_ashrrev_i32_e32 v97, 31, v96
	v_lshlrev_b64 v[98:99], 10, v[96:97]
	v_mad_i64_i32 v[96:97], s[74:75], v96, s10, 0
	v_lshl_add_u64 v[104:105], s[44:45], 0, v[98:99]
	v_lshl_add_u64 v[104:105], s[38:39], 1, v[104:105]
	v_cvt_pk_bf16_f32 v100, v92, v93
	v_cvt_pk_bf16_f32 v101, v94, v95
	v_cvt_pk_bf16_f32 v102, v88, v89
	v_cvt_pk_bf16_f32 v103, v90, v91
	v_lshl_add_u64 v[104:105], v[136:137], 1, v[104:105]
	global_store_dwordx4 v[104:105], v[100:103], off
	s_ashr_i32 s21, s21, 4
	v_lshl_add_u64 v[92:93], s[44:45], 0, v[98:99]
	v_lshl_add_u64 v[92:93], s[38:39], 1, v[92:93]
	v_cvt_pk_bf16_f32 v88, v84, v85
	v_cvt_pk_bf16_f32 v89, v86, v87
	v_cvt_pk_bf16_f32 v90, v80, v81
	v_cvt_pk_bf16_f32 v91, v82, v83
	v_lshl_add_u64 v[92:93], v[136:137], 1, v[92:93]
	global_store_dwordx4 v[92:93], v[88:91], off offset:256
	s_or_b32 s21, s57, 48
	v_or_b32_e32 v80, s21, v162
	v_ashrrev_i32_e32 v81, 31, v80
	v_lshlrev_b64 v[82:83], 10, v[80:81]
	v_mad_i64_i32 v[80:81], s[74:75], v80, s10, 0
	v_lshl_add_u64 v[88:89], s[44:45], 0, v[82:83]
	v_lshl_add_u64 v[88:89], s[38:39], 1, v[88:89]
	v_cvt_pk_bf16_f32 v84, v76, v77
	v_cvt_pk_bf16_f32 v85, v78, v79
	v_cvt_pk_bf16_f32 v86, v72, v73
	v_cvt_pk_bf16_f32 v87, v74, v75
	v_lshl_add_u64 v[88:89], v[136:137], 1, v[88:89]
	global_store_dwordx4 v[88:89], v[84:87], off
	s_ashr_i32 s21, s21, 4
	v_lshl_add_u64 v[76:77], s[44:45], 0, v[82:83]
	v_lshl_add_u64 v[76:77], s[38:39], 1, v[76:77]
	v_cvt_pk_bf16_f32 v72, v68, v69
	v_cvt_pk_bf16_f32 v73, v70, v71
	v_cvt_pk_bf16_f32 v74, v64, v65
	v_cvt_pk_bf16_f32 v75, v66, v67
	v_lshl_add_u64 v[76:77], v[136:137], 1, v[76:77]
	global_store_dwordx4 v[76:77], v[72:75], off offset:256
	s_add_i32 s21, s57, 0x80
	v_or_b32_e32 v64, s21, v162
	v_ashrrev_i32_e32 v65, 31, v64
	v_lshlrev_b64 v[66:67], 10, v[64:65]
	v_mad_i64_i32 v[64:65], s[74:75], v64, s10, 0
	v_lshl_add_u64 v[72:73], s[44:45], 0, v[66:67]
	v_lshl_add_u64 v[72:73], s[38:39], 1, v[72:73]
	v_cvt_pk_bf16_f32 v68, v60, v61
	v_cvt_pk_bf16_f32 v69, v62, v63
	v_cvt_pk_bf16_f32 v70, v56, v57
	v_cvt_pk_bf16_f32 v71, v58, v59
	v_lshl_add_u64 v[72:73], v[136:137], 1, v[72:73]
	global_store_dwordx4 v[72:73], v[68:71], off
	s_ashr_i32 s21, s21, 4
	v_lshl_add_u64 v[60:61], s[44:45], 0, v[66:67]
	v_lshl_add_u64 v[60:61], s[38:39], 1, v[60:61]
	v_cvt_pk_bf16_f32 v56, v52, v53
	v_cvt_pk_bf16_f32 v57, v54, v55
	v_cvt_pk_bf16_f32 v58, v48, v49
	v_cvt_pk_bf16_f32 v59, v50, v51
	v_lshl_add_u64 v[60:61], v[136:137], 1, v[60:61]
	global_store_dwordx4 v[60:61], v[56:59], off offset:256
	s_add_i32 s21, s57, 0x90
	v_or_b32_e32 v48, s21, v162
	v_ashrrev_i32_e32 v49, 31, v48
	v_lshlrev_b64 v[50:51], 10, v[48:49]
	v_mad_i64_i32 v[48:49], s[74:75], v48, s10, 0
	v_lshl_add_u64 v[56:57], s[44:45], 0, v[50:51]
	v_lshl_add_u64 v[56:57], s[38:39], 1, v[56:57]
	v_cvt_pk_bf16_f32 v52, v44, v45
	v_cvt_pk_bf16_f32 v53, v46, v47
	v_cvt_pk_bf16_f32 v54, v40, v41
	v_cvt_pk_bf16_f32 v55, v42, v43
	v_lshl_add_u64 v[56:57], v[136:137], 1, v[56:57]
	global_store_dwordx4 v[56:57], v[52:55], off
	s_ashr_i32 s21, s21, 4
	v_lshl_add_u64 v[44:45], s[44:45], 0, v[50:51]
	v_lshl_add_u64 v[44:45], s[38:39], 1, v[44:45]
	v_cvt_pk_bf16_f32 v40, v36, v37
	v_cvt_pk_bf16_f32 v41, v38, v39
	v_cvt_pk_bf16_f32 v42, v32, v33
	v_cvt_pk_bf16_f32 v43, v34, v35
	v_lshl_add_u64 v[44:45], v[136:137], 1, v[44:45]
	global_store_dwordx4 v[44:45], v[40:43], off offset:256
	s_add_i32 s21, s57, 0xa0
	v_or_b32_e32 v32, s21, v162
	v_ashrrev_i32_e32 v33, 31, v32
	v_lshlrev_b64 v[34:35], 10, v[32:33]
	v_mad_i64_i32 v[32:33], s[74:75], v32, s10, 0
	v_lshl_add_u64 v[40:41], s[44:45], 0, v[34:35]
	v_lshl_add_u64 v[40:41], s[38:39], 1, v[40:41]
	v_cvt_pk_bf16_f32 v36, v28, v29
	v_cvt_pk_bf16_f32 v37, v30, v31
	v_cvt_pk_bf16_f32 v38, v24, v25
	v_cvt_pk_bf16_f32 v39, v26, v27
	v_lshl_add_u64 v[40:41], v[136:137], 1, v[40:41]
	global_store_dwordx4 v[40:41], v[36:39], off
	s_ashr_i32 s21, s21, 4
	v_lshl_add_u64 v[28:29], s[44:45], 0, v[34:35]
	v_lshl_add_u64 v[28:29], s[38:39], 1, v[28:29]
	v_cvt_pk_bf16_f32 v24, v20, v21
	v_cvt_pk_bf16_f32 v25, v22, v23
	v_cvt_pk_bf16_f32 v26, v16, v17
	v_cvt_pk_bf16_f32 v27, v18, v19
	v_lshl_add_u64 v[28:29], v[136:137], 1, v[28:29]
	global_store_dwordx4 v[28:29], v[24:27], off offset:256
	s_addk_i32 s57, 0xb0
	v_or_b32_e32 v16, s57, v162
	v_ashrrev_i32_e32 v17, 31, v16
	v_lshlrev_b64 v[18:19], 10, v[16:17]
	v_mad_i64_i32 v[16:17], s[74:75], v16, s10, 0
	v_lshl_add_u64 v[24:25], s[44:45], 0, v[18:19]
	v_lshl_add_u64 v[24:25], s[38:39], 1, v[24:25]
	v_cvt_pk_bf16_f32 v20, v12, v13
	v_cvt_pk_bf16_f32 v21, v14, v15
	v_cvt_pk_bf16_f32 v22, v8, v9
	v_cvt_pk_bf16_f32 v23, v10, v11
	v_lshl_add_u64 v[24:25], v[136:137], 1, v[24:25]
	global_store_dwordx4 v[24:25], v[20:23], off
	s_ashr_i32 s21, s57, 4
	v_lshl_add_u64 v[12:13], s[44:45], 0, v[18:19]
	v_lshl_add_u64 v[12:13], s[38:39], 1, v[12:13]
	v_cvt_pk_bf16_f32 v8, v4, v5
	v_cvt_pk_bf16_f32 v9, v6, v7
	v_cvt_pk_bf16_f32 v10, v0, v1
	v_cvt_pk_bf16_f32 v11, v2, v3
	v_lshl_add_u64 v[12:13], v[136:137], 1, v[12:13]
	global_store_dwordx4 v[12:13], v[8:11], off offset:256
	s_andn2_b64 vcc, exec, s[4:5]
	s_mov_b64 s[4:5], -1
	s_cbranch_vccnz .LBB0_178
	s_andn2_b64 vcc, exec, s[40:41]
	s_cbranch_vccnz .LBB0_177
	s_barrier
	s_branch .LBB0_177
